# strategy 4 A/B: all 64 per-phase s_setprio flips in the GEMM K-loops deleted (on v054)
# speedup vs baseline: 1.0805x; 1.0082x over previous
.LBB0_241:
	ds_read_b128 v[146:149], v169
	ds_read_b128 v[150:153], v169 offset:1024
	ds_read_b128 v[154:157], v169 offset:2048
	ds_read_b128 v[158:161], v169 offset:3072
	s_add_u32 s18, s56, 0xfffc0080
	s_addc_u32 s62, s57, -1
	s_cmp_eq_u32 s35, 12
	s_cselect_b32 s81, s3, s62
	s_cselect_b32 s80, s7, s18
	s_cselect_b32 s63, s11, s17
	s_cselect_b32 s62, s13, s16
	v_lshl_add_u64 v[204:205], s[56:57], 0, v[138:139]
	s_add_i32 m0, s1, 0xc000
	ds_read_b128 v[162:165], v170
	ds_read_b128 v[176:179], v170 offset:1024
	ds_read_b128 v[180:183], v170 offset:2048
	ds_read_b128 v[184:187], v170 offset:3072
	ds_read_b128 v[188:191], v170 offset:4096
	ds_read_b128 v[192:195], v170 offset:5120
	ds_read_b128 v[196:199], v170 offset:6144
	ds_read_b128 v[200:203], v170 offset:7168
	global_load_lds_dwordx4 v[204:205], off
	v_lshl_add_u64 v[204:205], s[56:57], 0, v[140:141]
	s_add_i32 m0, s1, 0xe000
	s_nop 0
	global_load_lds_dwordx4 v[204:205], off
	s_waitcnt lgkmcnt(8)
	s_barrier
	s_waitcnt lgkmcnt(0)
	s_waitcnt lgkmcnt(0)
	v_mfma_f32_16x16x32_bf16 v[124:127], v[146:149], v[162:165], v[124:127]
	v_mfma_f32_16x16x32_bf16 v[120:123], v[154:157], v[162:165], v[120:123]
	v_mfma_f32_16x16x32_bf16 v[116:119], v[146:149], v[180:183], v[116:119]
	v_mfma_f32_16x16x32_bf16 v[112:115], v[154:157], v[180:183], v[112:115]
	v_mfma_f32_16x16x32_bf16 v[108:111], v[146:149], v[188:191], v[108:111]
	v_mfma_f32_16x16x32_bf16 v[104:107], v[154:157], v[188:191], v[104:107]
	v_mfma_f32_16x16x32_bf16 v[100:103], v[146:149], v[196:199], v[100:103]
	v_mfma_f32_16x16x32_bf16 v[96:99], v[154:157], v[196:199], v[96:99]
	v_mfma_f32_16x16x32_bf16 v[124:127], v[150:153], v[176:179], v[124:127]
	v_mfma_f32_16x16x32_bf16 v[120:123], v[158:161], v[176:179], v[120:123]
	v_mfma_f32_16x16x32_bf16 v[116:119], v[150:153], v[184:187], v[116:119]
	v_mfma_f32_16x16x32_bf16 v[112:115], v[158:161], v[184:187], v[112:115]
	v_mfma_f32_16x16x32_bf16 v[108:111], v[150:153], v[192:195], v[108:111]
	v_mfma_f32_16x16x32_bf16 v[104:107], v[158:161], v[192:195], v[104:107]
	v_mfma_f32_16x16x32_bf16 v[100:103], v[150:153], v[200:203], v[100:103]
	v_mfma_f32_16x16x32_bf16 v[96:99], v[158:161], v[200:203], v[96:99]
	s_barrier
	s_add_i32 s18, s74, s28
	v_lshl_add_u64 v[220:221], s[62:63], 0, v[130:131]
	s_mov_b32 m0, s18
	ds_read_b128 v[204:207], v171
	ds_read_b128 v[208:211], v171 offset:1024
	ds_read_b128 v[212:215], v171 offset:2048
	ds_read_b128 v[216:219], v171 offset:3072
	global_load_lds_dwordx4 v[220:221], off
	v_lshl_add_u64 v[222:223], s[62:63], 0, v[134:135]
	s_add_i32 m0, s18, 0x2000
	s_nop 0
	global_load_lds_dwordx4 v[222:223], off
	s_barrier
	s_waitcnt lgkmcnt(0)
	s_waitcnt lgkmcnt(0)
	v_mfma_f32_16x16x32_bf16 v[60:63], v[204:207], v[162:165], v[60:63]
	v_mfma_f32_16x16x32_bf16 v[56:59], v[212:215], v[162:165], v[56:59]
	v_mfma_f32_16x16x32_bf16 v[52:55], v[204:207], v[180:183], v[52:55]
	v_mfma_f32_16x16x32_bf16 v[48:51], v[212:215], v[180:183], v[48:51]
	v_mfma_f32_16x16x32_bf16 v[44:47], v[204:207], v[188:191], v[44:47]
	v_mfma_f32_16x16x32_bf16 v[40:43], v[212:215], v[188:191], v[40:43]
	v_mfma_f32_16x16x32_bf16 v[36:39], v[204:207], v[196:199], v[36:39]
	v_mfma_f32_16x16x32_bf16 v[32:35], v[212:215], v[196:199], v[32:35]
	v_mfma_f32_16x16x32_bf16 v[60:63], v[208:211], v[176:179], v[60:63]
	v_mfma_f32_16x16x32_bf16 v[56:59], v[216:219], v[176:179], v[56:59]
	v_mfma_f32_16x16x32_bf16 v[52:55], v[208:211], v[184:187], v[52:55]
	v_mfma_f32_16x16x32_bf16 v[48:51], v[216:219], v[184:187], v[48:51]
	v_mfma_f32_16x16x32_bf16 v[44:47], v[208:211], v[192:195], v[44:47]
	v_mfma_f32_16x16x32_bf16 v[40:43], v[216:219], v[192:195], v[40:43]
	v_mfma_f32_16x16x32_bf16 v[36:39], v[208:211], v[200:203], v[36:39]
	v_mfma_f32_16x16x32_bf16 v[32:35], v[216:219], v[200:203], v[32:35]
	s_mov_b32 m0, s1
	v_lshl_add_u64 v[226:227], s[80:81], 0, v[128:129]
	s_barrier
	ds_read_b128 v[162:165], v170 offset:16384
	ds_read_b128 v[176:179], v170 offset:17408
	ds_read_b128 v[180:183], v170 offset:18432
	ds_read_b128 v[184:187], v170 offset:19456
	ds_read_b128 v[188:191], v170 offset:20480
	ds_read_b128 v[192:195], v170 offset:21504
	ds_read_b128 v[196:199], v170 offset:22528
	ds_read_b128 v[200:203], v170 offset:23552
	global_load_lds_dwordx4 v[226:227], off
	v_lshl_add_u64 v[228:229], s[80:81], 0, v[132:133]
	s_mov_b32 m0, s29
	s_nop 0
	global_load_lds_dwordx4 v[228:229], off
	s_barrier
	s_waitcnt lgkmcnt(0)
	s_waitcnt lgkmcnt(0)
	v_mfma_f32_16x16x32_bf16 v[92:95], v[146:149], v[162:165], v[92:95]
	v_mfma_f32_16x16x32_bf16 v[88:91], v[154:157], v[162:165], v[88:91]
	v_mfma_f32_16x16x32_bf16 v[84:87], v[146:149], v[180:183], v[84:87]
	v_mfma_f32_16x16x32_bf16 v[80:83], v[154:157], v[180:183], v[80:83]
	v_mfma_f32_16x16x32_bf16 v[76:79], v[146:149], v[188:191], v[76:79]
	v_mfma_f32_16x16x32_bf16 v[72:75], v[154:157], v[188:191], v[72:75]
	v_mfma_f32_16x16x32_bf16 v[68:71], v[146:149], v[196:199], v[68:71]
	v_mfma_f32_16x16x32_bf16 v[64:67], v[154:157], v[196:199], v[64:67]
	v_mfma_f32_16x16x32_bf16 v[92:95], v[150:153], v[176:179], v[92:95]
	v_mfma_f32_16x16x32_bf16 v[88:91], v[158:161], v[176:179], v[88:91]
	v_mfma_f32_16x16x32_bf16 v[84:87], v[150:153], v[184:187], v[84:87]
	v_mfma_f32_16x16x32_bf16 v[80:83], v[158:161], v[184:187], v[80:83]
	v_mfma_f32_16x16x32_bf16 v[76:79], v[150:153], v[192:195], v[76:79]
	v_mfma_f32_16x16x32_bf16 v[72:75], v[158:161], v[192:195], v[72:75]
	v_mfma_f32_16x16x32_bf16 v[68:71], v[150:153], v[200:203], v[68:71]
	v_mfma_f32_16x16x32_bf16 v[64:67], v[158:161], v[200:203], v[64:67]
	s_barrier
	s_add_u32 s76, s62, 0x40000
	s_addc_u32 s77, s63, 0
	s_add_i32 s18, s75, s28
	v_lshl_add_u64 v[146:147], s[76:77], 0, v[130:131]
	s_mov_b32 m0, s18
	s_nop 0
	global_load_lds_dwordx4 v[146:147], off
	v_lshl_add_u64 v[146:147], s[76:77], 0, v[134:135]
	s_add_i32 m0, s18, 0x2000
	s_nop 0
	global_load_lds_dwordx4 v[146:147], off
	s_waitcnt vmcnt(6)
	s_barrier
	v_mfma_f32_16x16x32_bf16 v[28:31], v[204:207], v[162:165], v[28:31]
	v_mfma_f32_16x16x32_bf16 v[24:27], v[212:215], v[162:165], v[24:27]
	v_mfma_f32_16x16x32_bf16 v[20:23], v[204:207], v[180:183], v[20:23]
	v_mfma_f32_16x16x32_bf16 v[16:19], v[212:215], v[180:183], v[16:19]
	v_mfma_f32_16x16x32_bf16 v[12:15], v[204:207], v[188:191], v[12:15]
	v_mfma_f32_16x16x32_bf16 v[8:11], v[212:215], v[188:191], v[8:11]
	v_mfma_f32_16x16x32_bf16 v[4:7], v[204:207], v[196:199], v[4:7]
	v_mfma_f32_16x16x32_bf16 v[0:3], v[212:215], v[196:199], v[0:3]
	v_mfma_f32_16x16x32_bf16 v[28:31], v[208:211], v[176:179], v[28:31]
	v_mfma_f32_16x16x32_bf16 v[24:27], v[216:219], v[176:179], v[24:27]
	v_mfma_f32_16x16x32_bf16 v[20:23], v[208:211], v[184:187], v[20:23]
	v_mfma_f32_16x16x32_bf16 v[16:19], v[216:219], v[184:187], v[16:19]
	v_mfma_f32_16x16x32_bf16 v[12:15], v[208:211], v[192:195], v[12:15]
	v_mfma_f32_16x16x32_bf16 v[8:11], v[216:219], v[192:195], v[8:11]
	v_mfma_f32_16x16x32_bf16 v[4:7], v[208:211], v[200:203], v[4:7]
	v_mfma_f32_16x16x32_bf16 v[0:3], v[216:219], v[200:203], v[0:3]
	s_add_i32 s18, 0, 0x18000
	v_add_u32_e32 v136, s18, v167
	s_barrier
	ds_read_b128 v[146:149], v136
	ds_read_b128 v[150:153], v136 offset:1024
	ds_read_b128 v[154:157], v136 offset:2048
	ds_read_b128 v[158:161], v136 offset:3072
	s_add_u32 s76, s80, 0x40000
	s_addc_u32 s77, s81, 0
	s_mov_b32 m0, s68
	v_lshl_add_u64 v[204:205], s[76:77], 0, v[128:129]
	ds_read_b128 v[162:165], v170 offset:32768
	ds_read_b128 v[176:179], v170 offset:33792
	ds_read_b128 v[180:183], v170 offset:34816
	ds_read_b128 v[184:187], v170 offset:35840
	ds_read_b128 v[188:191], v170 offset:36864
	ds_read_b128 v[192:195], v170 offset:37888
	ds_read_b128 v[196:199], v170 offset:38912
	ds_read_b128 v[200:203], v170 offset:39936
	global_load_lds_dwordx4 v[204:205], off
	v_lshl_add_u64 v[204:205], s[76:77], 0, v[132:133]
	s_mov_b32 m0, s69
	s_nop 0
	global_load_lds_dwordx4 v[204:205], off
	s_waitcnt lgkmcnt(8)
	s_barrier
	s_waitcnt lgkmcnt(0)
	s_waitcnt lgkmcnt(0)
	v_mfma_f32_16x16x32_bf16 v[124:127], v[146:149], v[162:165], v[124:127]
	v_mfma_f32_16x16x32_bf16 v[120:123], v[154:157], v[162:165], v[120:123]
	v_mfma_f32_16x16x32_bf16 v[116:119], v[146:149], v[180:183], v[116:119]
	v_mfma_f32_16x16x32_bf16 v[112:115], v[154:157], v[180:183], v[112:115]
	v_mfma_f32_16x16x32_bf16 v[108:111], v[146:149], v[188:191], v[108:111]
	v_mfma_f32_16x16x32_bf16 v[104:107], v[154:157], v[188:191], v[104:107]
	v_mfma_f32_16x16x32_bf16 v[100:103], v[146:149], v[196:199], v[100:103]
	v_mfma_f32_16x16x32_bf16 v[96:99], v[154:157], v[196:199], v[96:99]
	v_mfma_f32_16x16x32_bf16 v[124:127], v[150:153], v[176:179], v[124:127]
	v_mfma_f32_16x16x32_bf16 v[120:123], v[158:161], v[176:179], v[120:123]
	v_mfma_f32_16x16x32_bf16 v[116:119], v[150:153], v[184:187], v[116:119]
	v_mfma_f32_16x16x32_bf16 v[112:115], v[158:161], v[184:187], v[112:115]
	v_mfma_f32_16x16x32_bf16 v[108:111], v[150:153], v[192:195], v[108:111]
	v_mfma_f32_16x16x32_bf16 v[104:107], v[158:161], v[192:195], v[104:107]
	v_mfma_f32_16x16x32_bf16 v[100:103], v[150:153], v[200:203], v[100:103]
	v_mfma_f32_16x16x32_bf16 v[96:99], v[158:161], v[200:203], v[96:99]
	s_barrier
	s_add_i32 s76, 0, 0x1c000
	s_add_i32 s18, s18, s28
	v_add_u32_e32 v136, s76, v167
	v_lshl_add_u64 v[220:221], v[220:221], 0, s[8:9]
	s_mov_b32 m0, s18
	ds_read_b128 v[204:207], v136
	ds_read_b128 v[208:211], v136 offset:1024
	ds_read_b128 v[212:215], v136 offset:2048
	ds_read_b128 v[216:219], v136 offset:3072
	global_load_lds_dwordx4 v[220:221], off
	v_lshl_add_u64 v[220:221], v[222:223], 0, s[8:9]
	s_add_i32 m0, s18, 0x2000
	s_nop 0
	global_load_lds_dwordx4 v[220:221], off
	s_barrier
	s_waitcnt lgkmcnt(0)
	s_waitcnt lgkmcnt(0)
	v_mfma_f32_16x16x32_bf16 v[60:63], v[204:207], v[162:165], v[60:63]
	v_mfma_f32_16x16x32_bf16 v[56:59], v[212:215], v[162:165], v[56:59]
	v_mfma_f32_16x16x32_bf16 v[52:55], v[204:207], v[180:183], v[52:55]
	v_mfma_f32_16x16x32_bf16 v[48:51], v[212:215], v[180:183], v[48:51]
	v_mfma_f32_16x16x32_bf16 v[44:47], v[204:207], v[188:191], v[44:47]
	v_mfma_f32_16x16x32_bf16 v[40:43], v[212:215], v[188:191], v[40:43]
	v_mfma_f32_16x16x32_bf16 v[36:39], v[204:207], v[196:199], v[36:39]
	v_mfma_f32_16x16x32_bf16 v[32:35], v[212:215], v[196:199], v[32:35]
	v_mfma_f32_16x16x32_bf16 v[60:63], v[208:211], v[176:179], v[60:63]
	v_mfma_f32_16x16x32_bf16 v[56:59], v[216:219], v[176:179], v[56:59]
	v_mfma_f32_16x16x32_bf16 v[52:55], v[208:211], v[184:187], v[52:55]
	v_mfma_f32_16x16x32_bf16 v[48:51], v[216:219], v[184:187], v[48:51]
	v_mfma_f32_16x16x32_bf16 v[44:47], v[208:211], v[192:195], v[44:47]
	v_mfma_f32_16x16x32_bf16 v[40:43], v[216:219], v[192:195], v[40:43]
	v_mfma_f32_16x16x32_bf16 v[36:39], v[208:211], v[200:203], v[36:39]
	v_mfma_f32_16x16x32_bf16 v[32:35], v[216:219], v[200:203], v[32:35]
	s_mov_b32 m0, s72
	v_lshl_add_u64 v[220:221], v[226:227], 0, s[8:9]
	s_barrier
	ds_read_b128 v[162:165], v170 offset:49152
	ds_read_b128 v[176:179], v170 offset:50176
	ds_read_b128 v[180:183], v170 offset:51200
	ds_read_b128 v[184:187], v170 offset:52224
	ds_read_b128 v[188:191], v170 offset:53248
	ds_read_b128 v[192:195], v170 offset:54272
	ds_read_b128 v[196:199], v170 offset:55296
	ds_read_b128 v[200:203], v170 offset:56320
	global_load_lds_dwordx4 v[220:221], off
	v_lshl_add_u64 v[220:221], v[228:229], 0, s[8:9]
	s_mov_b32 m0, s73
	s_nop 0
	global_load_lds_dwordx4 v[220:221], off
	s_barrier
	s_waitcnt lgkmcnt(0)
	s_waitcnt lgkmcnt(0)
	v_mfma_f32_16x16x32_bf16 v[92:95], v[146:149], v[162:165], v[92:95]
	v_mfma_f32_16x16x32_bf16 v[88:91], v[154:157], v[162:165], v[88:91]
	v_mfma_f32_16x16x32_bf16 v[84:87], v[146:149], v[180:183], v[84:87]
	v_mfma_f32_16x16x32_bf16 v[80:83], v[154:157], v[180:183], v[80:83]
	v_mfma_f32_16x16x32_bf16 v[76:79], v[146:149], v[188:191], v[76:79]
	v_mfma_f32_16x16x32_bf16 v[72:75], v[154:157], v[188:191], v[72:75]
	v_mfma_f32_16x16x32_bf16 v[68:71], v[146:149], v[196:199], v[68:71]
	v_mfma_f32_16x16x32_bf16 v[64:67], v[154:157], v[196:199], v[64:67]
	v_mfma_f32_16x16x32_bf16 v[92:95], v[150:153], v[176:179], v[92:95]
	v_mfma_f32_16x16x32_bf16 v[88:91], v[158:161], v[176:179], v[88:91]
	v_mfma_f32_16x16x32_bf16 v[84:87], v[150:153], v[184:187], v[84:87]
	v_mfma_f32_16x16x32_bf16 v[80:83], v[158:161], v[184:187], v[80:83]
	v_mfma_f32_16x16x32_bf16 v[76:79], v[150:153], v[192:195], v[76:79]
	v_mfma_f32_16x16x32_bf16 v[72:75], v[158:161], v[192:195], v[72:75]
	v_mfma_f32_16x16x32_bf16 v[68:71], v[150:153], v[200:203], v[68:71]
	v_mfma_f32_16x16x32_bf16 v[64:67], v[158:161], v[200:203], v[64:67]
	s_barrier
	s_add_u32 s62, s62, 0x40080
	s_addc_u32 s63, s63, 0
	s_add_i32 s18, s76, s28
	v_lshl_add_u64 v[146:147], s[62:63], 0, v[130:131]
	s_mov_b32 m0, s18
	s_nop 0
	global_load_lds_dwordx4 v[146:147], off
	v_lshl_add_u64 v[146:147], s[62:63], 0, v[134:135]
	s_add_i32 m0, s18, 0x2000
	s_nop 0
	global_load_lds_dwordx4 v[146:147], off
	s_waitcnt vmcnt(6)
	s_barrier
	v_mfma_f32_16x16x32_bf16 v[28:31], v[204:207], v[162:165], v[28:31]
	v_mfma_f32_16x16x32_bf16 v[24:27], v[212:215], v[162:165], v[24:27]
	v_mfma_f32_16x16x32_bf16 v[20:23], v[204:207], v[180:183], v[20:23]
	v_mfma_f32_16x16x32_bf16 v[16:19], v[212:215], v[180:183], v[16:19]
	v_mfma_f32_16x16x32_bf16 v[12:15], v[204:207], v[188:191], v[12:15]
	v_mfma_f32_16x16x32_bf16 v[8:11], v[212:215], v[188:191], v[8:11]
	v_mfma_f32_16x16x32_bf16 v[4:7], v[204:207], v[196:199], v[4:7]
	v_mfma_f32_16x16x32_bf16 v[0:3], v[212:215], v[196:199], v[0:3]
	v_mfma_f32_16x16x32_bf16 v[28:31], v[208:211], v[176:179], v[28:31]
	v_mfma_f32_16x16x32_bf16 v[24:27], v[216:219], v[176:179], v[24:27]
	v_mfma_f32_16x16x32_bf16 v[20:23], v[208:211], v[184:187], v[20:23]
	v_mfma_f32_16x16x32_bf16 v[16:19], v[216:219], v[184:187], v[16:19]
	v_mfma_f32_16x16x32_bf16 v[12:15], v[208:211], v[192:195], v[12:15]
	v_mfma_f32_16x16x32_bf16 v[8:11], v[216:219], v[192:195], v[8:11]
	v_mfma_f32_16x16x32_bf16 v[4:7], v[208:211], v[200:203], v[4:7]
	v_mfma_f32_16x16x32_bf16 v[0:3], v[216:219], v[200:203], v[0:3]
	s_add_i32 s35, s35, 2
	s_add_u32 s56, s56, 0x100
	s_addc_u32 s57, s57, 0
	s_add_u32 s16, s16, 0x100
	s_addc_u32 s17, s17, 0
	s_cmp_gt_u32 s35, 13
	s_barrier
	s_cbranch_scc0 .LBB0_241
	s_and_b32 s3, s0, -4
	v_lshl_add_u32 v146, s6, 8, v166
	s_cmp_lg_u32 s3, 4
	s_mov_b64 s[6:7], -1
	s_cbranch_scc0 .LBB0_756
	s_cmp_gt_i32 s0, 1
	s_cselect_b64 s[16:17], -1, 0
	s_cmp_eq_u32 s0, 10
	s_cselect_b64 vcc, -1, 0
	v_cndmask_b32_e32 v136, 1.0, v172, vcc
	s_and_b64 vcc, exec, s[16:17]
	s_cbranch_vccz .LBB0_245
	v_mul_f32_e32 v148, v136, v124
	s_mov_b64 s[6:7], 0

.LBB0_1066:
	ds_read_b128 v[112:115], v169
	ds_read_b128 v[116:119], v169 offset:1024
	ds_read_b128 v[120:123], v169 offset:2048
	ds_read_b128 v[124:127], v169 offset:3072
	s_add_u32 s18, s56, 0xfffc0080
	s_addc_u32 s62, s57, -1
	s_cmp_eq_u32 s74, 12
	s_cselect_b32 s65, s43, s62
	s_cselect_b32 s64, s68, s18
	s_cselect_b32 s63, s41, s73
	s_cselect_b32 s62, s69, s70
	v_lshl_add_u64 v[164:165], s[56:57], 0, v[152:153]
	s_add_i32 m0, s17, 0xc000
	ds_read_b128 v[160:163], v170
	ds_read_b128 v[172:175], v170 offset:1024
	ds_read_b128 v[176:179], v170 offset:2048
	ds_read_b128 v[180:183], v170 offset:3072
	ds_read_b128 v[184:187], v170 offset:4096
	ds_read_b128 v[188:191], v170 offset:5120
	ds_read_b128 v[192:195], v170 offset:6144
	ds_read_b128 v[196:199], v170 offset:7168
	global_load_lds_dwordx4 v[164:165], off
	v_lshl_add_u64 v[164:165], s[56:57], 0, v[154:155]
	s_add_i32 m0, s17, 0xe000
	s_nop 0
	global_load_lds_dwordx4 v[164:165], off
	s_waitcnt lgkmcnt(8)
	s_barrier
	s_waitcnt lgkmcnt(0)
	s_waitcnt lgkmcnt(0)
	v_mfma_f32_16x16x32_bf16 v[140:143], v[112:115], v[160:163], v[140:143]
	v_mfma_f32_16x16x32_bf16 v[136:139], v[120:123], v[160:163], v[136:139]
	v_mfma_f32_16x16x32_bf16 v[108:111], v[112:115], v[176:179], v[108:111]
	v_mfma_f32_16x16x32_bf16 v[104:107], v[120:123], v[176:179], v[104:107]
	v_mfma_f32_16x16x32_bf16 v[92:95], v[112:115], v[184:187], v[92:95]
	v_mfma_f32_16x16x32_bf16 v[88:91], v[120:123], v[184:187], v[88:91]
	v_mfma_f32_16x16x32_bf16 v[76:79], v[112:115], v[192:195], v[76:79]
	v_mfma_f32_16x16x32_bf16 v[72:75], v[120:123], v[192:195], v[72:75]
	v_mfma_f32_16x16x32_bf16 v[140:143], v[116:119], v[172:175], v[140:143]
	v_mfma_f32_16x16x32_bf16 v[136:139], v[124:127], v[172:175], v[136:139]
	v_mfma_f32_16x16x32_bf16 v[108:111], v[116:119], v[180:183], v[108:111]
	v_mfma_f32_16x16x32_bf16 v[104:107], v[124:127], v[180:183], v[104:107]
	v_mfma_f32_16x16x32_bf16 v[92:95], v[116:119], v[188:191], v[92:95]
	v_mfma_f32_16x16x32_bf16 v[88:91], v[124:127], v[188:191], v[88:91]
	v_mfma_f32_16x16x32_bf16 v[76:79], v[116:119], v[196:199], v[76:79]
	v_mfma_f32_16x16x32_bf16 v[72:75], v[124:127], v[196:199], v[72:75]
	s_barrier
	s_add_i32 s18, s59, s16
	v_lshl_add_u64 v[164:165], s[62:63], 0, v[148:149]
	s_mov_b32 m0, s18
	ds_read_b128 v[200:203], v171
	ds_read_b128 v[204:207], v171 offset:1024
	ds_read_b128 v[208:211], v171 offset:2048
	ds_read_b128 v[212:215], v171 offset:3072
	global_load_lds_dwordx4 v[164:165], off
	v_lshl_add_u64 v[216:217], s[62:63], 0, v[144:145]
	s_add_i32 m0, s18, 0x2000
	s_nop 0
	global_load_lds_dwordx4 v[216:217], off
	s_barrier
	s_waitcnt lgkmcnt(0)
	s_waitcnt lgkmcnt(0)
	v_mfma_f32_16x16x32_bf16 v[132:135], v[200:203], v[160:163], v[132:135]
	v_mfma_f32_16x16x32_bf16 v[128:131], v[208:211], v[160:163], v[128:131]
	v_mfma_f32_16x16x32_bf16 v[100:103], v[200:203], v[176:179], v[100:103]
	v_mfma_f32_16x16x32_bf16 v[96:99], v[208:211], v[176:179], v[96:99]
	v_mfma_f32_16x16x32_bf16 v[84:87], v[200:203], v[184:187], v[84:87]
	v_mfma_f32_16x16x32_bf16 v[80:83], v[208:211], v[184:187], v[80:83]
	v_mfma_f32_16x16x32_bf16 v[68:71], v[200:203], v[192:195], v[68:71]
	v_mfma_f32_16x16x32_bf16 v[64:67], v[208:211], v[192:195], v[64:67]
	v_mfma_f32_16x16x32_bf16 v[132:135], v[204:207], v[172:175], v[132:135]
	v_mfma_f32_16x16x32_bf16 v[128:131], v[212:215], v[172:175], v[128:131]
	v_mfma_f32_16x16x32_bf16 v[100:103], v[204:207], v[180:183], v[100:103]
	v_mfma_f32_16x16x32_bf16 v[96:99], v[212:215], v[180:183], v[96:99]
	v_mfma_f32_16x16x32_bf16 v[84:87], v[204:207], v[188:191], v[84:87]
	v_mfma_f32_16x16x32_bf16 v[80:83], v[212:215], v[188:191], v[80:83]
	v_mfma_f32_16x16x32_bf16 v[68:71], v[204:207], v[196:199], v[68:71]
	v_mfma_f32_16x16x32_bf16 v[64:67], v[212:215], v[196:199], v[64:67]
	s_mov_b32 m0, s17
	v_lshl_add_u64 v[218:219], s[64:65], 0, v[150:151]
	s_barrier
	ds_read_b128 v[160:163], v170 offset:16384
	ds_read_b128 v[172:175], v170 offset:17408
	ds_read_b128 v[176:179], v170 offset:18432
	ds_read_b128 v[180:183], v170 offset:19456
	ds_read_b128 v[184:187], v170 offset:20480
	ds_read_b128 v[188:191], v170 offset:21504
	ds_read_b128 v[192:195], v170 offset:22528
	ds_read_b128 v[196:199], v170 offset:23552
	global_load_lds_dwordx4 v[218:219], off
	v_lshl_add_u64 v[220:221], s[64:65], 0, v[146:147]
	s_mov_b32 m0, s19
	s_nop 0
	global_load_lds_dwordx4 v[220:221], off
	s_barrier
	s_waitcnt lgkmcnt(0)
	s_waitcnt lgkmcnt(0)
	v_mfma_f32_16x16x32_bf16 v[60:63], v[112:115], v[160:163], v[60:63]
	v_mfma_f32_16x16x32_bf16 v[56:59], v[120:123], v[160:163], v[56:59]
	v_mfma_f32_16x16x32_bf16 v[52:55], v[112:115], v[176:179], v[52:55]
	v_mfma_f32_16x16x32_bf16 v[44:47], v[120:123], v[176:179], v[44:47]
	v_mfma_f32_16x16x32_bf16 v[36:39], v[112:115], v[184:187], v[36:39]
	v_mfma_f32_16x16x32_bf16 v[28:31], v[120:123], v[184:187], v[28:31]
	v_mfma_f32_16x16x32_bf16 v[20:23], v[112:115], v[192:195], v[20:23]
	v_mfma_f32_16x16x32_bf16 v[12:15], v[120:123], v[192:195], v[12:15]
	v_mfma_f32_16x16x32_bf16 v[60:63], v[116:119], v[172:175], v[60:63]
	v_mfma_f32_16x16x32_bf16 v[56:59], v[124:127], v[172:175], v[56:59]
	v_mfma_f32_16x16x32_bf16 v[52:55], v[116:119], v[180:183], v[52:55]
	v_mfma_f32_16x16x32_bf16 v[44:47], v[124:127], v[180:183], v[44:47]
	v_mfma_f32_16x16x32_bf16 v[36:39], v[116:119], v[188:191], v[36:39]
	v_mfma_f32_16x16x32_bf16 v[28:31], v[124:127], v[188:191], v[28:31]
	v_mfma_f32_16x16x32_bf16 v[20:23], v[116:119], v[196:199], v[20:23]
	v_mfma_f32_16x16x32_bf16 v[12:15], v[124:127], v[196:199], v[12:15]
	s_barrier
	s_add_u32 s76, s62, 0x40000
	s_addc_u32 s77, s63, 0
	s_add_i32 s18, s66, s16
	v_lshl_add_u64 v[112:113], s[76:77], 0, v[148:149]
	s_mov_b32 m0, s18
	s_nop 0
	global_load_lds_dwordx4 v[112:113], off
	v_lshl_add_u64 v[112:113], s[76:77], 0, v[144:145]
	s_add_i32 m0, s18, 0x2000
	s_nop 0
	global_load_lds_dwordx4 v[112:113], off
	s_waitcnt vmcnt(6)
	s_barrier
	v_mfma_f32_16x16x32_bf16 v[48:51], v[200:203], v[160:163], v[48:51]
	v_mfma_f32_16x16x32_bf16 v[40:43], v[208:211], v[160:163], v[40:43]
	v_mfma_f32_16x16x32_bf16 v[32:35], v[200:203], v[176:179], v[32:35]
	v_mfma_f32_16x16x32_bf16 v[24:27], v[208:211], v[176:179], v[24:27]
	v_mfma_f32_16x16x32_bf16 v[16:19], v[200:203], v[184:187], v[16:19]
	v_mfma_f32_16x16x32_bf16 v[8:11], v[208:211], v[184:187], v[8:11]
	v_mfma_f32_16x16x32_bf16 v[4:7], v[200:203], v[192:195], v[4:7]
	v_mfma_f32_16x16x32_bf16 v[0:3], v[208:211], v[192:195], v[0:3]
	v_mfma_f32_16x16x32_bf16 v[48:51], v[204:207], v[172:175], v[48:51]
	v_mfma_f32_16x16x32_bf16 v[40:43], v[212:215], v[172:175], v[40:43]
	v_mfma_f32_16x16x32_bf16 v[32:35], v[204:207], v[180:183], v[32:35]
	v_mfma_f32_16x16x32_bf16 v[24:27], v[212:215], v[180:183], v[24:27]
	v_mfma_f32_16x16x32_bf16 v[16:19], v[204:207], v[188:191], v[16:19]
	v_mfma_f32_16x16x32_bf16 v[8:11], v[212:215], v[188:191], v[8:11]
	v_mfma_f32_16x16x32_bf16 v[4:7], v[204:207], v[196:199], v[4:7]
	v_mfma_f32_16x16x32_bf16 v[0:3], v[212:215], v[196:199], v[0:3]
	s_add_i32 s18, 0, 0x18000
	v_add_u32_e32 v124, s18, v167
	s_barrier
	ds_read_b128 v[112:115], v124
	ds_read_b128 v[116:119], v124 offset:1024
	ds_read_b128 v[120:123], v124 offset:2048
	ds_read_b128 v[124:127], v124 offset:3072
	s_add_u32 s64, s64, 0x40000
	s_addc_u32 s65, s65, 0
	s_mov_b32 m0, s28
	v_lshl_add_u64 v[200:201], s[64:65], 0, v[150:151]
	ds_read_b128 v[160:163], v170 offset:32768
	ds_read_b128 v[172:175], v170 offset:33792
	ds_read_b128 v[176:179], v170 offset:34816
	ds_read_b128 v[180:183], v170 offset:35840
	ds_read_b128 v[184:187], v170 offset:36864
	ds_read_b128 v[188:191], v170 offset:37888
	ds_read_b128 v[192:195], v170 offset:38912
	ds_read_b128 v[196:199], v170 offset:39936
	global_load_lds_dwordx4 v[200:201], off
	v_lshl_add_u64 v[200:201], s[64:65], 0, v[146:147]
	s_mov_b32 m0, s29
	s_nop 0
	global_load_lds_dwordx4 v[200:201], off
	s_waitcnt lgkmcnt(8)
	s_barrier
	s_waitcnt lgkmcnt(0)
	s_waitcnt lgkmcnt(0)
	v_mfma_f32_16x16x32_bf16 v[140:143], v[112:115], v[160:163], v[140:143]
	v_mfma_f32_16x16x32_bf16 v[136:139], v[120:123], v[160:163], v[136:139]
	v_mfma_f32_16x16x32_bf16 v[108:111], v[112:115], v[176:179], v[108:111]
	v_mfma_f32_16x16x32_bf16 v[104:107], v[120:123], v[176:179], v[104:107]
	v_mfma_f32_16x16x32_bf16 v[92:95], v[112:115], v[184:187], v[92:95]
	v_mfma_f32_16x16x32_bf16 v[88:91], v[120:123], v[184:187], v[88:91]
	v_mfma_f32_16x16x32_bf16 v[76:79], v[112:115], v[192:195], v[76:79]
	v_mfma_f32_16x16x32_bf16 v[72:75], v[120:123], v[192:195], v[72:75]
	v_mfma_f32_16x16x32_bf16 v[140:143], v[116:119], v[172:175], v[140:143]
	v_mfma_f32_16x16x32_bf16 v[136:139], v[124:127], v[172:175], v[136:139]
	v_mfma_f32_16x16x32_bf16 v[108:111], v[116:119], v[180:183], v[108:111]
	v_mfma_f32_16x16x32_bf16 v[104:107], v[124:127], v[180:183], v[104:107]
	v_mfma_f32_16x16x32_bf16 v[92:95], v[116:119], v[188:191], v[92:95]
	v_mfma_f32_16x16x32_bf16 v[88:91], v[124:127], v[188:191], v[88:91]
	v_mfma_f32_16x16x32_bf16 v[76:79], v[116:119], v[196:199], v[76:79]
	v_mfma_f32_16x16x32_bf16 v[72:75], v[124:127], v[196:199], v[72:75]
	s_barrier
	s_add_i32 s64, 0, 0x1c000
	s_add_i32 s18, s18, s16
	v_add_u32_e32 v212, s64, v167
	v_lshl_add_u64 v[164:165], v[164:165], 0, s[0:1]
	s_mov_b32 m0, s18
	ds_read_b128 v[200:203], v212
	ds_read_b128 v[204:207], v212 offset:1024
	ds_read_b128 v[208:211], v212 offset:2048
	ds_read_b128 v[212:215], v212 offset:3072
	global_load_lds_dwordx4 v[164:165], off
	v_lshl_add_u64 v[164:165], v[216:217], 0, s[0:1]
	s_add_i32 m0, s18, 0x2000
	s_nop 0
	global_load_lds_dwordx4 v[164:165], off
	s_barrier
	s_waitcnt lgkmcnt(0)
	s_waitcnt lgkmcnt(0)
	v_mfma_f32_16x16x32_bf16 v[132:135], v[200:203], v[160:163], v[132:135]
	v_mfma_f32_16x16x32_bf16 v[128:131], v[208:211], v[160:163], v[128:131]
	v_mfma_f32_16x16x32_bf16 v[100:103], v[200:203], v[176:179], v[100:103]
	v_mfma_f32_16x16x32_bf16 v[96:99], v[208:211], v[176:179], v[96:99]
	v_mfma_f32_16x16x32_bf16 v[84:87], v[200:203], v[184:187], v[84:87]
	v_mfma_f32_16x16x32_bf16 v[80:83], v[208:211], v[184:187], v[80:83]
	v_mfma_f32_16x16x32_bf16 v[68:71], v[200:203], v[192:195], v[68:71]
	v_mfma_f32_16x16x32_bf16 v[64:67], v[208:211], v[192:195], v[64:67]
	v_mfma_f32_16x16x32_bf16 v[132:135], v[204:207], v[172:175], v[132:135]
	v_mfma_f32_16x16x32_bf16 v[128:131], v[212:215], v[172:175], v[128:131]
	v_mfma_f32_16x16x32_bf16 v[100:103], v[204:207], v[180:183], v[100:103]
	v_mfma_f32_16x16x32_bf16 v[96:99], v[212:215], v[180:183], v[96:99]
	v_mfma_f32_16x16x32_bf16 v[84:87], v[204:207], v[188:191], v[84:87]
	v_mfma_f32_16x16x32_bf16 v[80:83], v[212:215], v[188:191], v[80:83]
	v_mfma_f32_16x16x32_bf16 v[68:71], v[204:207], v[196:199], v[68:71]
	v_mfma_f32_16x16x32_bf16 v[64:67], v[212:215], v[196:199], v[64:67]
	s_mov_b32 m0, s53
	v_lshl_add_u64 v[164:165], v[218:219], 0, s[0:1]
	s_barrier
	ds_read_b128 v[160:163], v170 offset:49152
	ds_read_b128 v[172:175], v170 offset:50176
	ds_read_b128 v[176:179], v170 offset:51200
	ds_read_b128 v[180:183], v170 offset:52224
	ds_read_b128 v[184:187], v170 offset:53248
	ds_read_b128 v[188:191], v170 offset:54272
	ds_read_b128 v[192:195], v170 offset:55296
	ds_read_b128 v[196:199], v170 offset:56320
	global_load_lds_dwordx4 v[164:165], off
	v_lshl_add_u64 v[164:165], v[220:221], 0, s[0:1]
	s_mov_b32 m0, s58
	s_nop 0
	global_load_lds_dwordx4 v[164:165], off
	s_barrier
	s_waitcnt lgkmcnt(0)
	s_waitcnt lgkmcnt(0)
	v_mfma_f32_16x16x32_bf16 v[60:63], v[112:115], v[160:163], v[60:63]
	v_mfma_f32_16x16x32_bf16 v[56:59], v[120:123], v[160:163], v[56:59]
	v_mfma_f32_16x16x32_bf16 v[52:55], v[112:115], v[176:179], v[52:55]
	v_mfma_f32_16x16x32_bf16 v[44:47], v[120:123], v[176:179], v[44:47]
	v_mfma_f32_16x16x32_bf16 v[36:39], v[112:115], v[184:187], v[36:39]
	v_mfma_f32_16x16x32_bf16 v[28:31], v[120:123], v[184:187], v[28:31]
	v_mfma_f32_16x16x32_bf16 v[20:23], v[112:115], v[192:195], v[20:23]
	v_mfma_f32_16x16x32_bf16 v[12:15], v[120:123], v[192:195], v[12:15]
	v_mfma_f32_16x16x32_bf16 v[60:63], v[116:119], v[172:175], v[60:63]
	v_mfma_f32_16x16x32_bf16 v[56:59], v[124:127], v[172:175], v[56:59]
	v_mfma_f32_16x16x32_bf16 v[52:55], v[116:119], v[180:183], v[52:55]
	v_mfma_f32_16x16x32_bf16 v[44:47], v[124:127], v[180:183], v[44:47]
	v_mfma_f32_16x16x32_bf16 v[36:39], v[116:119], v[188:191], v[36:39]
	v_mfma_f32_16x16x32_bf16 v[28:31], v[124:127], v[188:191], v[28:31]
	v_mfma_f32_16x16x32_bf16 v[20:23], v[116:119], v[196:199], v[20:23]
	v_mfma_f32_16x16x32_bf16 v[12:15], v[124:127], v[196:199], v[12:15]
	s_barrier
	s_add_u32 s62, s62, 0x40080
	s_addc_u32 s63, s63, 0
	s_add_i32 s18, s64, s16
	v_lshl_add_u64 v[112:113], s[62:63], 0, v[148:149]
	s_mov_b32 m0, s18
	s_nop 0
	global_load_lds_dwordx4 v[112:113], off
	v_lshl_add_u64 v[112:113], s[62:63], 0, v[144:145]
	s_add_i32 m0, s18, 0x2000
	s_nop 0
	global_load_lds_dwordx4 v[112:113], off
	s_waitcnt vmcnt(6)
	s_barrier
	v_mfma_f32_16x16x32_bf16 v[48:51], v[200:203], v[160:163], v[48:51]
	v_mfma_f32_16x16x32_bf16 v[40:43], v[208:211], v[160:163], v[40:43]
	v_mfma_f32_16x16x32_bf16 v[32:35], v[200:203], v[176:179], v[32:35]
	v_mfma_f32_16x16x32_bf16 v[24:27], v[208:211], v[176:179], v[24:27]
	v_mfma_f32_16x16x32_bf16 v[16:19], v[200:203], v[184:187], v[16:19]
	v_mfma_f32_16x16x32_bf16 v[8:11], v[208:211], v[184:187], v[8:11]
	v_mfma_f32_16x16x32_bf16 v[4:7], v[200:203], v[192:195], v[4:7]
	v_mfma_f32_16x16x32_bf16 v[0:3], v[208:211], v[192:195], v[0:3]
	v_mfma_f32_16x16x32_bf16 v[48:51], v[204:207], v[172:175], v[48:51]
	v_mfma_f32_16x16x32_bf16 v[40:43], v[212:215], v[172:175], v[40:43]
	v_mfma_f32_16x16x32_bf16 v[32:35], v[204:207], v[180:183], v[32:35]
	v_mfma_f32_16x16x32_bf16 v[24:27], v[212:215], v[180:183], v[24:27]
	v_mfma_f32_16x16x32_bf16 v[16:19], v[204:207], v[188:191], v[16:19]
	v_mfma_f32_16x16x32_bf16 v[8:11], v[212:215], v[188:191], v[8:11]
	v_mfma_f32_16x16x32_bf16 v[4:7], v[204:207], v[196:199], v[4:7]
	v_mfma_f32_16x16x32_bf16 v[0:3], v[212:215], v[196:199], v[0:3]
	s_add_i32 s74, s74, 2
	s_add_u32 s56, s56, 0x100
	s_addc_u32 s57, s57, 0
	s_add_u32 s70, s70, 0x100
	s_addc_u32 s73, s73, 0
	s_cmp_gt_u32 s74, 13
	s_barrier
	s_cbranch_scc0 .LBB0_1066
	s_sub_i32 s18, s52, 32
	s_lshr_b32 s18, s18, 2
	s_mulk_i32 s18, 0xc00
	s_addk_i32 s18, 0xc00
	s_cmp_gt_i32 s52, 31
	s_cselect_b32 s56, s18, 0
	s_ashr_i32 s57, s56, 31
	s_lshl_b64 s[56:57], s[56:57], 2
	v_lshl_or_b32 v160, s67, 8, v168
	s_add_u32 s56, s24, s56
	s_addc_u32 s57, s25, s57
	v_ashrrev_i32_e32 v161, 31, v160
	v_lshl_add_u64 v[112:113], v[160:161], 2, s[56:57]
	s_mov_b64 s[56:57], 0x1502000
	s_mov_b32 s18, 0x1502000
	v_lshl_add_u64 v[116:117], v[112:113], 0, s[56:57]
	v_add_co_u32_e32 v112, vcc, s18, v112
	v_lshl_add_u32 v164, s52, 8, v166
	s_nop 0
	v_addc_co_u32_e32 v113, vcc, 0, v113, vcc
	global_load_dwordx4 v[120:123], v[112:113], off
	global_load_dwordx4 v[124:127], v[116:117], off offset:16
	s_nop 0
	global_load_dwordx4 v[112:115], v[116:117], off offset:528
	s_nop 0
	global_load_dwordx4 v[116:119], v[116:117], off offset:512
	v_ashrrev_i32_e32 v165, 31, v164
	v_lshlrev_b64 v[162:163], 11, v[164:165]
	v_lshl_add_u64 v[172:173], s[10:11], 0, v[162:163]
	v_lshlrev_b64 v[162:163], 1, v[160:161]
	v_lshl_add_u64 v[160:161], v[172:173], 0, v[162:163]
	s_mov_b32 s18, 0x40000
	s_mov_b64 s[56:57], 0x40000
	s_mov_b32 s67, s40
	s_mov_b32 s52, s42
	s_mov_b64 s[62:63], s[48:49]
	s_waitcnt vmcnt(0)
	v_pk_mul_f32 v[142:143], v[142:143], v[122:123]
	v_pk_mul_f32 v[140:141], v[140:141], v[120:121]
	v_pk_mul_f32 v[172:173], v[138:139], v[126:127]
	v_pk_mul_f32 v[138:139], v[136:137], v[124:125]
	v_cvt_pk_bf16_f32 v136, v140, v141
	v_cvt_pk_bf16_f32 v137, v142, v143
	v_cvt_pk_bf16_f32 v138, v138, v139
	v_cvt_pk_bf16_f32 v139, v172, v173
	global_store_dwordx4 v[160:161], v[136:139], off
	v_pk_mul_f32 v[134:135], v[134:135], v[118:119]
	v_pk_mul_f32 v[132:133], v[132:133], v[116:117]
	v_pk_mul_f32 v[136:137], v[130:131], v[114:115]
	v_pk_mul_f32 v[130:131], v[128:129], v[112:113]
	v_cvt_pk_bf16_f32 v128, v132, v133
	v_cvt_pk_bf16_f32 v129, v134, v135
	v_cvt_pk_bf16_f32 v130, v130, v131
	v_cvt_pk_bf16_f32 v131, v136, v137
	global_store_dwordx4 v[160:161], v[128:131], off offset:256
	v_pk_mul_f32 v[110:111], v[110:111], v[122:123]
	v_pk_mul_f32 v[108:109], v[108:109], v[120:121]
	v_or_b32_e32 v128, 16, v164
	v_ashrrev_i32_e32 v129, 31, v128
	v_lshlrev_b64 v[128:129], 11, v[128:129]
	v_lshl_add_u64 v[128:129], s[10:11], 0, v[128:129]
	v_pk_mul_f32 v[130:131], v[106:107], v[126:127]
	v_pk_mul_f32 v[106:107], v[104:105], v[124:125]
	v_lshl_add_u64 v[128:129], v[128:129], 0, v[162:163]
	v_cvt_pk_bf16_f32 v104, v108, v109
	v_cvt_pk_bf16_f32 v105, v110, v111
	v_cvt_pk_bf16_f32 v106, v106, v107
	v_cvt_pk_bf16_f32 v107, v130, v131
	global_store_dwordx4 v[128:129], v[104:107], off
	v_pk_mul_f32 v[102:103], v[102:103], v[118:119]
	v_pk_mul_f32 v[100:101], v[100:101], v[116:117]
	v_pk_mul_f32 v[104:105], v[98:99], v[114:115]
	v_pk_mul_f32 v[98:99], v[96:97], v[112:113]
	v_cvt_pk_bf16_f32 v96, v100, v101
	v_cvt_pk_bf16_f32 v97, v102, v103
	v_cvt_pk_bf16_f32 v98, v98, v99
	v_cvt_pk_bf16_f32 v99, v104, v105
	global_store_dwordx4 v[128:129], v[96:99], off offset:256
	v_pk_mul_f32 v[94:95], v[94:95], v[122:123]
	v_pk_mul_f32 v[92:93], v[92:93], v[120:121]
	v_or_b32_e32 v96, 32, v164
	v_ashrrev_i32_e32 v97, 31, v96
	v_lshlrev_b64 v[96:97], 11, v[96:97]
	v_lshl_add_u64 v[96:97], s[10:11], 0, v[96:97]
	v_pk_mul_f32 v[98:99], v[90:91], v[126:127]
	v_pk_mul_f32 v[90:91], v[88:89], v[124:125]
	v_lshl_add_u64 v[96:97], v[96:97], 0, v[162:163]
	v_cvt_pk_bf16_f32 v88, v92, v93
	v_cvt_pk_bf16_f32 v89, v94, v95
	v_cvt_pk_bf16_f32 v90, v90, v91
	v_cvt_pk_bf16_f32 v91, v98, v99
	global_store_dwordx4 v[96:97], v[88:91], off
	v_pk_mul_f32 v[86:87], v[86:87], v[118:119]
	v_pk_mul_f32 v[84:85], v[84:85], v[116:117]
	v_pk_mul_f32 v[88:89], v[82:83], v[114:115]
	v_pk_mul_f32 v[82:83], v[80:81], v[112:113]
	v_cvt_pk_bf16_f32 v80, v84, v85
	v_cvt_pk_bf16_f32 v81, v86, v87
	v_cvt_pk_bf16_f32 v82, v82, v83
	v_cvt_pk_bf16_f32 v83, v88, v89
	global_store_dwordx4 v[96:97], v[80:83], off offset:256
	v_pk_mul_f32 v[78:79], v[78:79], v[122:123]
	v_pk_mul_f32 v[76:77], v[76:77], v[120:121]
	v_or_b32_e32 v80, 48, v164
	v_ashrrev_i32_e32 v81, 31, v80
	v_lshlrev_b64 v[80:81], 11, v[80:81]
	v_lshl_add_u64 v[80:81], s[10:11], 0, v[80:81]
	v_pk_mul_f32 v[82:83], v[74:75], v[126:127]
	v_pk_mul_f32 v[74:75], v[72:73], v[124:125]
	v_lshl_add_u64 v[80:81], v[80:81], 0, v[162:163]
	v_cvt_pk_bf16_f32 v72, v76, v77
	v_cvt_pk_bf16_f32 v73, v78, v79
	v_cvt_pk_bf16_f32 v74, v74, v75
	v_cvt_pk_bf16_f32 v75, v82, v83
	global_store_dwordx4 v[80:81], v[72:75], off
	v_pk_mul_f32 v[70:71], v[70:71], v[118:119]
	v_pk_mul_f32 v[68:69], v[68:69], v[116:117]
	v_pk_mul_f32 v[72:73], v[66:67], v[114:115]
	v_pk_mul_f32 v[66:67], v[64:65], v[112:113]
	v_cvt_pk_bf16_f32 v64, v68, v69
	v_cvt_pk_bf16_f32 v65, v70, v71
	v_cvt_pk_bf16_f32 v66, v66, v67
	v_cvt_pk_bf16_f32 v67, v72, v73
	v_pk_mul_f32 v[60:61], v[60:61], v[120:121]
	global_store_dwordx4 v[80:81], v[64:67], off offset:256
	v_pk_mul_f32 v[62:63], v[62:63], v[122:123]
	v_pk_mul_f32 v[50:51], v[50:51], v[118:119]
	v_pk_mul_f32 v[66:67], v[58:59], v[126:127]
	v_pk_mul_f32 v[58:59], v[56:57], v[124:125]
	v_cvt_pk_bf16_f32 v56, v60, v61
	v_add_co_u32_e32 v60, vcc, s18, v160
	v_cvt_pk_bf16_f32 v57, v62, v63
	v_cvt_pk_bf16_f32 v58, v58, v59
	v_cvt_pk_bf16_f32 v59, v66, v67
	v_addc_co_u32_e32 v61, vcc, 0, v161, vcc
	global_store_dwordx4 v[60:61], v[56:59], off
	v_pk_mul_f32 v[48:49], v[48:49], v[116:117]
	v_lshl_add_u64 v[64:65], v[160:161], 0, s[56:57]
	v_pk_mul_f32 v[56:57], v[42:43], v[114:115]
	v_pk_mul_f32 v[42:43], v[40:41], v[112:113]
	v_cvt_pk_bf16_f32 v40, v48, v49
	v_cvt_pk_bf16_f32 v41, v50, v51
	v_cvt_pk_bf16_f32 v42, v42, v43
	v_cvt_pk_bf16_f32 v43, v56, v57
	global_store_dwordx4 v[64:65], v[40:43], off offset:256
	v_pk_mul_f32 v[44:45], v[44:45], v[124:125]
	s_mov_b32 s18, 0x48000
	v_pk_mul_f32 v[42:43], v[54:55], v[122:123]
	v_pk_mul_f32 v[40:41], v[52:53], v[120:121]
	v_pk_mul_f32 v[46:47], v[46:47], v[126:127]
	v_cvt_pk_bf16_f32 v40, v40, v41
	v_cvt_pk_bf16_f32 v41, v42, v43
	v_cvt_pk_bf16_f32 v42, v44, v45
	v_add_co_u32_e32 v44, vcc, s18, v160
	v_cvt_pk_bf16_f32 v43, v46, v47
	s_nop 0
	v_addc_co_u32_e32 v45, vcc, 0, v161, vcc
	s_mov_b64 s[56:57], 0x48000
	global_store_dwordx4 v[44:45], v[40:43], off
	v_pk_mul_f32 v[34:35], v[34:35], v[118:119]
	v_pk_mul_f32 v[32:33], v[32:33], v[116:117]
	v_pk_mul_f32 v[40:41], v[26:27], v[114:115]
	v_pk_mul_f32 v[26:27], v[24:25], v[112:113]
	v_lshl_add_u64 v[48:49], v[160:161], 0, s[56:57]
	v_cvt_pk_bf16_f32 v24, v32, v33
	v_cvt_pk_bf16_f32 v25, v34, v35
	v_cvt_pk_bf16_f32 v26, v26, v27
	v_cvt_pk_bf16_f32 v27, v40, v41
	global_store_dwordx4 v[48:49], v[24:27], off offset:256
	v_pk_mul_f32 v[28:29], v[28:29], v[124:125]
	s_mov_b32 s18, 0x50000
	v_pk_mul_f32 v[26:27], v[38:39], v[122:123]
	v_pk_mul_f32 v[24:25], v[36:37], v[120:121]
	v_pk_mul_f32 v[30:31], v[30:31], v[126:127]
	v_cvt_pk_bf16_f32 v24, v24, v25
	v_cvt_pk_bf16_f32 v25, v26, v27
	v_cvt_pk_bf16_f32 v26, v28, v29
	v_add_co_u32_e32 v28, vcc, s18, v160
	v_cvt_pk_bf16_f32 v27, v30, v31
	s_nop 0
	v_addc_co_u32_e32 v29, vcc, 0, v161, vcc
	s_mov_b64 s[56:57], 0x50000
	global_store_dwordx4 v[28:29], v[24:27], off
	v_pk_mul_f32 v[18:19], v[18:19], v[118:119]
	v_pk_mul_f32 v[16:17], v[16:17], v[116:117]
	v_pk_mul_f32 v[24:25], v[10:11], v[114:115]
	v_pk_mul_f32 v[10:11], v[8:9], v[112:113]
	v_lshl_add_u64 v[32:33], v[160:161], 0, s[56:57]
	v_cvt_pk_bf16_f32 v8, v16, v17
	v_cvt_pk_bf16_f32 v9, v18, v19
	v_cvt_pk_bf16_f32 v10, v10, v11
	v_cvt_pk_bf16_f32 v11, v24, v25
	global_store_dwordx4 v[32:33], v[8:11], off offset:256
	v_pk_mul_f32 v[12:13], v[12:13], v[124:125]
	s_mov_b32 s18, 0x58000
	v_pk_mul_f32 v[10:11], v[22:23], v[122:123]
	v_pk_mul_f32 v[8:9], v[20:21], v[120:121]
	v_pk_mul_f32 v[14:15], v[14:15], v[126:127]
	v_cvt_pk_bf16_f32 v8, v8, v9
	v_cvt_pk_bf16_f32 v9, v10, v11
	v_cvt_pk_bf16_f32 v10, v12, v13
	v_add_co_u32_e32 v12, vcc, s18, v160
	v_cvt_pk_bf16_f32 v11, v14, v15
	s_nop 0
	v_addc_co_u32_e32 v13, vcc, 0, v161, vcc
	s_mov_b64 s[56:57], 0x58000
	global_store_dwordx4 v[12:13], v[8:11], off
	v_pk_mul_f32 v[6:7], v[6:7], v[118:119]
	v_pk_mul_f32 v[4:5], v[4:5], v[116:117]
	v_pk_mul_f32 v[8:9], v[2:3], v[114:115]
	v_pk_mul_f32 v[2:3], v[0:1], v[112:113]
	v_lshl_add_u64 v[16:17], v[160:161], 0, s[56:57]
	v_cvt_pk_bf16_f32 v0, v4, v5
	v_cvt_pk_bf16_f32 v1, v6, v7
	v_cvt_pk_bf16_f32 v2, v2, v3
	v_cvt_pk_bf16_f32 v3, v8, v9
	s_and_b64 vcc, exec, s[4:5]
	s_mov_b64 s[56:57], s[46:47]
	global_store_dwordx4 v[16:17], v[0:3], off offset:256
	s_cbranch_vccz .LBB0_1063
	s_waitcnt vmcnt(0)
	s_cmpk_gt_u32 s3, 0xff
	s_cbranch_scc1 .LBB0_1070
	s_barrier

.LBB0_1264:
	ds_read_b128 v[150:153], v162
	ds_read_b128 v[166:169], v162 offset:1024
	ds_read_b128 v[170:173], v162 offset:2048
	ds_read_b128 v[174:177], v162 offset:3072
	s_add_u32 s18, s56, 0xfffc0080
	s_addc_u32 s62, s57, -1
	s_cmp_eq_u32 s74, 12
	s_cselect_b32 s65, s7, s62
	s_cselect_b32 s64, s35, s18
	s_cselect_b32 s63, s47, s73
	s_cselect_b32 s62, s49, s70
	v_lshl_add_u64 v[154:155], s[56:57], 0, v[142:143]
	s_add_i32 m0, s17, 0xc000
	ds_read_b128 v[178:181], v163
	ds_read_b128 v[182:185], v163 offset:1024
	ds_read_b128 v[186:189], v163 offset:2048
	ds_read_b128 v[190:193], v163 offset:3072
	ds_read_b128 v[194:197], v163 offset:4096
	ds_read_b128 v[198:201], v163 offset:5120
	ds_read_b128 v[202:205], v163 offset:6144
	ds_read_b128 v[206:209], v163 offset:7168
	global_load_lds_dwordx4 v[154:155], off
	v_lshl_add_u64 v[154:155], s[56:57], 0, v[144:145]
	s_add_i32 m0, s17, 0xe000
	s_nop 0
	global_load_lds_dwordx4 v[154:155], off
	s_waitcnt lgkmcnt(8)
	s_barrier
	s_waitcnt lgkmcnt(0)
	s_waitcnt lgkmcnt(0)
	v_mfma_f32_16x16x32_bf16 v[124:127], v[150:153], v[178:181], v[124:127]
	v_mfma_f32_16x16x32_bf16 v[120:123], v[170:173], v[178:181], v[120:123]
	v_mfma_f32_16x16x32_bf16 v[116:119], v[150:153], v[186:189], v[116:119]
	v_mfma_f32_16x16x32_bf16 v[112:115], v[170:173], v[186:189], v[112:115]
	v_mfma_f32_16x16x32_bf16 v[108:111], v[150:153], v[194:197], v[108:111]
	v_mfma_f32_16x16x32_bf16 v[104:107], v[170:173], v[194:197], v[104:107]
	v_mfma_f32_16x16x32_bf16 v[100:103], v[150:153], v[202:205], v[100:103]
	v_mfma_f32_16x16x32_bf16 v[96:99], v[170:173], v[202:205], v[96:99]
	v_mfma_f32_16x16x32_bf16 v[124:127], v[166:169], v[182:185], v[124:127]
	v_mfma_f32_16x16x32_bf16 v[120:123], v[174:177], v[182:185], v[120:123]
	v_mfma_f32_16x16x32_bf16 v[116:119], v[166:169], v[190:193], v[116:119]
	v_mfma_f32_16x16x32_bf16 v[112:115], v[174:177], v[190:193], v[112:115]
	v_mfma_f32_16x16x32_bf16 v[108:111], v[166:169], v[198:201], v[108:111]
	v_mfma_f32_16x16x32_bf16 v[104:107], v[174:177], v[198:201], v[104:107]
	v_mfma_f32_16x16x32_bf16 v[100:103], v[166:169], v[206:209], v[100:103]
	v_mfma_f32_16x16x32_bf16 v[96:99], v[174:177], v[206:209], v[96:99]
	s_barrier
	s_add_i32 s18, s68, s3
	v_lshl_add_u64 v[154:155], s[62:63], 0, v[130:131]
	s_mov_b32 m0, s18
	ds_read_b128 v[210:213], v164
	ds_read_b128 v[214:217], v164 offset:1024
	ds_read_b128 v[218:221], v164 offset:2048
	ds_read_b128 v[226:229], v164 offset:3072
	global_load_lds_dwordx4 v[154:155], off
	v_lshl_add_u64 v[222:223], s[62:63], 0, v[134:135]
	s_add_i32 m0, s18, 0x2000
	s_nop 0
	global_load_lds_dwordx4 v[222:223], off
	s_barrier
	s_waitcnt lgkmcnt(0)
	s_waitcnt lgkmcnt(0)
	v_mfma_f32_16x16x32_bf16 v[60:63], v[210:213], v[178:181], v[60:63]
	v_mfma_f32_16x16x32_bf16 v[56:59], v[218:221], v[178:181], v[56:59]
	v_mfma_f32_16x16x32_bf16 v[52:55], v[210:213], v[186:189], v[52:55]
	v_mfma_f32_16x16x32_bf16 v[48:51], v[218:221], v[186:189], v[48:51]
	v_mfma_f32_16x16x32_bf16 v[44:47], v[210:213], v[194:197], v[44:47]
	v_mfma_f32_16x16x32_bf16 v[40:43], v[218:221], v[194:197], v[40:43]
	v_mfma_f32_16x16x32_bf16 v[36:39], v[210:213], v[202:205], v[36:39]
	v_mfma_f32_16x16x32_bf16 v[32:35], v[218:221], v[202:205], v[32:35]
	v_mfma_f32_16x16x32_bf16 v[60:63], v[214:217], v[182:185], v[60:63]
	v_mfma_f32_16x16x32_bf16 v[56:59], v[226:229], v[182:185], v[56:59]
	v_mfma_f32_16x16x32_bf16 v[52:55], v[214:217], v[190:193], v[52:55]
	v_mfma_f32_16x16x32_bf16 v[48:51], v[226:229], v[190:193], v[48:51]
	v_mfma_f32_16x16x32_bf16 v[44:47], v[214:217], v[198:201], v[44:47]
	v_mfma_f32_16x16x32_bf16 v[40:43], v[226:229], v[198:201], v[40:43]
	v_mfma_f32_16x16x32_bf16 v[36:39], v[214:217], v[206:209], v[36:39]
	v_mfma_f32_16x16x32_bf16 v[32:35], v[226:229], v[206:209], v[32:35]
	s_mov_b32 m0, s17
	v_lshl_add_u64 v[230:231], s[64:65], 0, v[128:129]
	s_barrier
	ds_read_b128 v[178:181], v163 offset:16384
	ds_read_b128 v[182:185], v163 offset:17408
	ds_read_b128 v[186:189], v163 offset:18432
	ds_read_b128 v[190:193], v163 offset:19456
	ds_read_b128 v[194:197], v163 offset:20480
	ds_read_b128 v[198:201], v163 offset:21504
	ds_read_b128 v[202:205], v163 offset:22528
	ds_read_b128 v[206:209], v163 offset:23552
	global_load_lds_dwordx4 v[230:231], off
	v_lshl_add_u64 v[232:233], s[64:65], 0, v[132:133]
	s_mov_b32 m0, s19
	s_nop 0
	global_load_lds_dwordx4 v[232:233], off
	s_barrier
	s_waitcnt lgkmcnt(0)
	s_waitcnt lgkmcnt(0)
	v_mfma_f32_16x16x32_bf16 v[92:95], v[150:153], v[178:181], v[92:95]
	v_mfma_f32_16x16x32_bf16 v[88:91], v[170:173], v[178:181], v[88:91]
	v_mfma_f32_16x16x32_bf16 v[84:87], v[150:153], v[186:189], v[84:87]
	v_mfma_f32_16x16x32_bf16 v[80:83], v[170:173], v[186:189], v[80:83]
	v_mfma_f32_16x16x32_bf16 v[76:79], v[150:153], v[194:197], v[76:79]
	v_mfma_f32_16x16x32_bf16 v[72:75], v[170:173], v[194:197], v[72:75]
	v_mfma_f32_16x16x32_bf16 v[68:71], v[150:153], v[202:205], v[68:71]
	v_mfma_f32_16x16x32_bf16 v[64:67], v[170:173], v[202:205], v[64:67]
	v_mfma_f32_16x16x32_bf16 v[92:95], v[166:169], v[182:185], v[92:95]
	v_mfma_f32_16x16x32_bf16 v[88:91], v[174:177], v[182:185], v[88:91]
	v_mfma_f32_16x16x32_bf16 v[84:87], v[166:169], v[190:193], v[84:87]
	v_mfma_f32_16x16x32_bf16 v[80:83], v[174:177], v[190:193], v[80:83]
	v_mfma_f32_16x16x32_bf16 v[76:79], v[166:169], v[198:201], v[76:79]
	v_mfma_f32_16x16x32_bf16 v[72:75], v[174:177], v[198:201], v[72:75]
	v_mfma_f32_16x16x32_bf16 v[68:71], v[166:169], v[206:209], v[68:71]
	v_mfma_f32_16x16x32_bf16 v[64:67], v[174:177], v[206:209], v[64:67]
	s_barrier
	s_add_u32 s76, s62, 0x40000
	s_addc_u32 s77, s63, 0
	s_add_i32 s18, s69, s3
	v_lshl_add_u64 v[150:151], s[76:77], 0, v[130:131]
	s_mov_b32 m0, s18
	s_nop 0
	global_load_lds_dwordx4 v[150:151], off
	v_lshl_add_u64 v[150:151], s[76:77], 0, v[134:135]
	s_add_i32 m0, s18, 0x2000
	s_nop 0
	global_load_lds_dwordx4 v[150:151], off
	s_waitcnt vmcnt(6)
	s_barrier
	v_mfma_f32_16x16x32_bf16 v[28:31], v[210:213], v[178:181], v[28:31]
	v_mfma_f32_16x16x32_bf16 v[24:27], v[218:221], v[178:181], v[24:27]
	v_mfma_f32_16x16x32_bf16 v[20:23], v[210:213], v[186:189], v[20:23]
	v_mfma_f32_16x16x32_bf16 v[16:19], v[218:221], v[186:189], v[16:19]
	v_mfma_f32_16x16x32_bf16 v[12:15], v[210:213], v[194:197], v[12:15]
	v_mfma_f32_16x16x32_bf16 v[8:11], v[218:221], v[194:197], v[8:11]
	v_mfma_f32_16x16x32_bf16 v[4:7], v[210:213], v[202:205], v[4:7]
	v_mfma_f32_16x16x32_bf16 v[0:3], v[218:221], v[202:205], v[0:3]
	v_mfma_f32_16x16x32_bf16 v[28:31], v[214:217], v[182:185], v[28:31]
	v_mfma_f32_16x16x32_bf16 v[24:27], v[226:229], v[182:185], v[24:27]
	v_mfma_f32_16x16x32_bf16 v[20:23], v[214:217], v[190:193], v[20:23]
	v_mfma_f32_16x16x32_bf16 v[16:19], v[226:229], v[190:193], v[16:19]
	v_mfma_f32_16x16x32_bf16 v[12:15], v[214:217], v[198:201], v[12:15]
	v_mfma_f32_16x16x32_bf16 v[8:11], v[226:229], v[198:201], v[8:11]
	v_mfma_f32_16x16x32_bf16 v[4:7], v[214:217], v[206:209], v[4:7]
	v_mfma_f32_16x16x32_bf16 v[0:3], v[226:229], v[206:209], v[0:3]
	s_add_i32 s18, 0, 0x18000
	v_add_u32_e32 v136, s18, v157
	s_barrier
	ds_read_b128 v[150:153], v136
	ds_read_b128 v[166:169], v136 offset:1024
	ds_read_b128 v[170:173], v136 offset:2048
	ds_read_b128 v[174:177], v136 offset:3072
	s_add_u32 s64, s64, 0x40000
	s_addc_u32 s65, s65, 0
	s_mov_b32 m0, s28
	v_lshl_add_u64 v[210:211], s[64:65], 0, v[128:129]
	ds_read_b128 v[178:181], v163 offset:32768
	ds_read_b128 v[182:185], v163 offset:33792
	ds_read_b128 v[186:189], v163 offset:34816
	ds_read_b128 v[190:193], v163 offset:35840
	ds_read_b128 v[194:197], v163 offset:36864
	ds_read_b128 v[198:201], v163 offset:37888
	ds_read_b128 v[202:205], v163 offset:38912
	ds_read_b128 v[206:209], v163 offset:39936
	global_load_lds_dwordx4 v[210:211], off
	v_lshl_add_u64 v[210:211], s[64:65], 0, v[132:133]
	s_mov_b32 m0, s29
	s_nop 0
	global_load_lds_dwordx4 v[210:211], off
	s_waitcnt lgkmcnt(8)
	s_barrier
	s_waitcnt lgkmcnt(0)
	s_waitcnt lgkmcnt(0)
	v_mfma_f32_16x16x32_bf16 v[124:127], v[150:153], v[178:181], v[124:127]
	v_mfma_f32_16x16x32_bf16 v[120:123], v[170:173], v[178:181], v[120:123]
	v_mfma_f32_16x16x32_bf16 v[116:119], v[150:153], v[186:189], v[116:119]
	v_mfma_f32_16x16x32_bf16 v[112:115], v[170:173], v[186:189], v[112:115]
	v_mfma_f32_16x16x32_bf16 v[108:111], v[150:153], v[194:197], v[108:111]
	v_mfma_f32_16x16x32_bf16 v[104:107], v[170:173], v[194:197], v[104:107]
	v_mfma_f32_16x16x32_bf16 v[100:103], v[150:153], v[202:205], v[100:103]
	v_mfma_f32_16x16x32_bf16 v[96:99], v[170:173], v[202:205], v[96:99]
	v_mfma_f32_16x16x32_bf16 v[124:127], v[166:169], v[182:185], v[124:127]
	v_mfma_f32_16x16x32_bf16 v[120:123], v[174:177], v[182:185], v[120:123]
	v_mfma_f32_16x16x32_bf16 v[116:119], v[166:169], v[190:193], v[116:119]
	v_mfma_f32_16x16x32_bf16 v[112:115], v[174:177], v[190:193], v[112:115]
	v_mfma_f32_16x16x32_bf16 v[108:111], v[166:169], v[198:201], v[108:111]
	v_mfma_f32_16x16x32_bf16 v[104:107], v[174:177], v[198:201], v[104:107]
	v_mfma_f32_16x16x32_bf16 v[100:103], v[166:169], v[206:209], v[100:103]
	v_mfma_f32_16x16x32_bf16 v[96:99], v[174:177], v[206:209], v[96:99]
	s_barrier
	s_add_i32 s64, 0, 0x1c000
	s_add_i32 s18, s18, s3
	v_add_u32_e32 v136, s64, v157
	v_lshl_add_u64 v[154:155], v[154:155], 0, s[36:37]
	s_mov_b32 m0, s18
	ds_read_b128 v[210:213], v136
	ds_read_b128 v[214:217], v136 offset:1024
	ds_read_b128 v[218:221], v136 offset:2048
	ds_read_b128 v[226:229], v136 offset:3072
	global_load_lds_dwordx4 v[154:155], off
	v_lshl_add_u64 v[154:155], v[222:223], 0, s[36:37]
	s_add_i32 m0, s18, 0x2000
	s_nop 0
	global_load_lds_dwordx4 v[154:155], off
	s_barrier
	s_waitcnt lgkmcnt(0)
	s_waitcnt lgkmcnt(0)
	v_mfma_f32_16x16x32_bf16 v[60:63], v[210:213], v[178:181], v[60:63]
	v_mfma_f32_16x16x32_bf16 v[56:59], v[218:221], v[178:181], v[56:59]
	v_mfma_f32_16x16x32_bf16 v[52:55], v[210:213], v[186:189], v[52:55]
	v_mfma_f32_16x16x32_bf16 v[48:51], v[218:221], v[186:189], v[48:51]
	v_mfma_f32_16x16x32_bf16 v[44:47], v[210:213], v[194:197], v[44:47]
	v_mfma_f32_16x16x32_bf16 v[40:43], v[218:221], v[194:197], v[40:43]
	v_mfma_f32_16x16x32_bf16 v[36:39], v[210:213], v[202:205], v[36:39]
	v_mfma_f32_16x16x32_bf16 v[32:35], v[218:221], v[202:205], v[32:35]
	v_mfma_f32_16x16x32_bf16 v[60:63], v[214:217], v[182:185], v[60:63]
	v_mfma_f32_16x16x32_bf16 v[56:59], v[226:229], v[182:185], v[56:59]
	v_mfma_f32_16x16x32_bf16 v[52:55], v[214:217], v[190:193], v[52:55]
	v_mfma_f32_16x16x32_bf16 v[48:51], v[226:229], v[190:193], v[48:51]
	v_mfma_f32_16x16x32_bf16 v[44:47], v[214:217], v[198:201], v[44:47]
	v_mfma_f32_16x16x32_bf16 v[40:43], v[226:229], v[198:201], v[40:43]
	v_mfma_f32_16x16x32_bf16 v[36:39], v[214:217], v[206:209], v[36:39]
	v_mfma_f32_16x16x32_bf16 v[32:35], v[226:229], v[206:209], v[32:35]
	s_mov_b32 m0, s59
	v_lshl_add_u64 v[154:155], v[230:231], 0, s[36:37]
	s_barrier
	ds_read_b128 v[178:181], v163 offset:49152
	ds_read_b128 v[182:185], v163 offset:50176
	ds_read_b128 v[186:189], v163 offset:51200
	ds_read_b128 v[190:193], v163 offset:52224
	ds_read_b128 v[194:197], v163 offset:53248
	ds_read_b128 v[198:201], v163 offset:54272
	ds_read_b128 v[202:205], v163 offset:55296
	ds_read_b128 v[206:209], v163 offset:56320
	global_load_lds_dwordx4 v[154:155], off
	v_lshl_add_u64 v[154:155], v[232:233], 0, s[36:37]
	s_mov_b32 m0, s66
	s_nop 0
	global_load_lds_dwordx4 v[154:155], off
	s_barrier
	s_waitcnt lgkmcnt(0)
	s_waitcnt lgkmcnt(0)
	v_mfma_f32_16x16x32_bf16 v[92:95], v[150:153], v[178:181], v[92:95]
	v_mfma_f32_16x16x32_bf16 v[88:91], v[170:173], v[178:181], v[88:91]
	v_mfma_f32_16x16x32_bf16 v[84:87], v[150:153], v[186:189], v[84:87]
	v_mfma_f32_16x16x32_bf16 v[80:83], v[170:173], v[186:189], v[80:83]
	v_mfma_f32_16x16x32_bf16 v[76:79], v[150:153], v[194:197], v[76:79]
	v_mfma_f32_16x16x32_bf16 v[72:75], v[170:173], v[194:197], v[72:75]
	v_mfma_f32_16x16x32_bf16 v[68:71], v[150:153], v[202:205], v[68:71]
	v_mfma_f32_16x16x32_bf16 v[64:67], v[170:173], v[202:205], v[64:67]
	v_mfma_f32_16x16x32_bf16 v[92:95], v[166:169], v[182:185], v[92:95]
	v_mfma_f32_16x16x32_bf16 v[88:91], v[174:177], v[182:185], v[88:91]
	v_mfma_f32_16x16x32_bf16 v[84:87], v[166:169], v[190:193], v[84:87]
	v_mfma_f32_16x16x32_bf16 v[80:83], v[174:177], v[190:193], v[80:83]
	v_mfma_f32_16x16x32_bf16 v[76:79], v[166:169], v[198:201], v[76:79]
	v_mfma_f32_16x16x32_bf16 v[72:75], v[174:177], v[198:201], v[72:75]
	v_mfma_f32_16x16x32_bf16 v[68:71], v[166:169], v[206:209], v[68:71]
	v_mfma_f32_16x16x32_bf16 v[64:67], v[174:177], v[206:209], v[64:67]
	s_barrier
	s_add_u32 s62, s62, 0x40080
	s_addc_u32 s63, s63, 0
	s_add_i32 s18, s64, s3
	v_lshl_add_u64 v[150:151], s[62:63], 0, v[130:131]
	s_mov_b32 m0, s18
	s_nop 0
	global_load_lds_dwordx4 v[150:151], off
	v_lshl_add_u64 v[150:151], s[62:63], 0, v[134:135]
	s_add_i32 m0, s18, 0x2000
	s_nop 0
	global_load_lds_dwordx4 v[150:151], off
	s_waitcnt vmcnt(6)
	s_barrier
	v_mfma_f32_16x16x32_bf16 v[28:31], v[210:213], v[178:181], v[28:31]
	v_mfma_f32_16x16x32_bf16 v[24:27], v[218:221], v[178:181], v[24:27]
	v_mfma_f32_16x16x32_bf16 v[20:23], v[210:213], v[186:189], v[20:23]
	v_mfma_f32_16x16x32_bf16 v[16:19], v[218:221], v[186:189], v[16:19]
	v_mfma_f32_16x16x32_bf16 v[12:15], v[210:213], v[194:197], v[12:15]
	v_mfma_f32_16x16x32_bf16 v[8:11], v[218:221], v[194:197], v[8:11]
	v_mfma_f32_16x16x32_bf16 v[4:7], v[210:213], v[202:205], v[4:7]
	v_mfma_f32_16x16x32_bf16 v[0:3], v[218:221], v[202:205], v[0:3]
	v_mfma_f32_16x16x32_bf16 v[28:31], v[214:217], v[182:185], v[28:31]
	v_mfma_f32_16x16x32_bf16 v[24:27], v[226:229], v[182:185], v[24:27]
	v_mfma_f32_16x16x32_bf16 v[20:23], v[214:217], v[190:193], v[20:23]
	v_mfma_f32_16x16x32_bf16 v[16:19], v[226:229], v[190:193], v[16:19]
	v_mfma_f32_16x16x32_bf16 v[12:15], v[214:217], v[198:201], v[12:15]
	v_mfma_f32_16x16x32_bf16 v[8:11], v[226:229], v[198:201], v[8:11]
	v_mfma_f32_16x16x32_bf16 v[4:7], v[214:217], v[206:209], v[4:7]
	v_mfma_f32_16x16x32_bf16 v[0:3], v[226:229], v[206:209], v[0:3]
	s_add_i32 s74, s74, 2
	s_add_u32 s56, s56, 0x100
	s_addc_u32 s57, s57, 0
	s_add_u32 s70, s70, 0x100
	s_addc_u32 s73, s73, 0
	s_cmp_gt_u32 s74, 13
	s_barrier
	s_cbranch_scc0 .LBB0_1264
	s_lshl_b32 s47, s6, 8
	s_add_i32 s47, s47, s58
	s_cmp_lt_i32 s54, 8
	s_cselect_b64 s[56:57], -1, 0
	s_cmp_gt_i32 s6, 31
	s_cselect_b64 s[6:7], -1, 0
	s_and_b64 s[56:57], s[56:57], s[6:7]
	v_cndmask_b32_e64 v136, 0, 1, s[56:57]
	v_cmp_ne_u32_e64 s[6:7], 1, v136
	s_andn2_b64 vcc, exec, s[56:57]
	s_bfe_u32 s35, s47, 0x40006
	s_cbranch_vccnz .LBB0_1267
	v_mov_b32_e32 v136, s35
	v_cndmask_b32_e64 v136, v156, v136, s[0:1]
	v_lshlrev_b32_e32 v136, 7, v136
	v_lshl_add_u64 v[150:151], v[138:139], 0, v[136:137]
	v_lshl_add_u64 v[154:155], v[140:141], 0, v[136:137]
	global_load_dwordx4 v[150:153], v[150:151], off
	s_nop 0
	global_load_dwordx4 v[166:169], v[154:155], off
	s_waitcnt vmcnt(0)
	v_pk_mul_f32 v[154:155], v[124:125], v[150:151]
	v_pk_mul_f32 v[170:171], v[124:125], v[166:167] op_sel:[1,0] op_sel_hi:[0,0]
	v_pk_mul_f32 v[166:167], v[126:127], v[166:167] op_sel:[1,1] op_sel_hi:[0,1]
	v_pk_mul_f32 v[172:173], v[120:121], v[168:169] op_sel:[1,0] op_sel_hi:[0,0]
	v_mov_b32_e32 v168, v153
	v_mul_f32_e32 v136, v123, v169
	v_mul_f32_e32 v174, v123, v153
	v_pk_fma_f32 v[124:125], v[124:125], v[150:151], v[170:171] op_sel_hi:[1,0,1]
	v_pk_fma_f32 v[176:177], v[126:127], v[150:151], v[166:167] op_sel:[0,1,0] neg_lo:[0,0,1] neg_hi:[0,0,1]
	v_pk_fma_f32 v[126:127], v[126:127], v[150:151], v[166:167] op_sel:[0,1,0]
	v_pk_fma_f32 v[150:151], v[120:121], v[152:153], v[172:173] op_sel_hi:[1,0,1] neg_lo:[0,0,1] neg_hi:[0,0,1]
	v_pk_fma_f32 v[120:121], v[120:121], v[152:153], v[172:173] op_sel_hi:[1,0,1]
	v_mov_b32_e32 v152, v169
	v_pk_fma_f32 v[166:167], v[122:123], v[168:169], v[136:137] op_sel_hi:[1,1,0] neg_lo:[0,0,1] neg_hi:[0,0,1]
	v_pk_fma_f32 v[152:153], v[122:123], v[152:153], v[174:175] op_sel_hi:[1,1,0]
	v_sub_f32_e32 v124, v154, v170
	v_mov_b32_e32 v126, v176
	v_mov_b32_e32 v120, v150
	v_mov_b32_e32 v122, v166
	v_mov_b32_e32 v123, v152

.LBB0_1499:
	ds_read_b128 v[128:131], v163
	ds_read_b128 v[132:135], v163 offset:1024
	ds_read_b128 v[136:139], v163 offset:2048
	ds_read_b128 v[140:143], v163 offset:3072
	s_add_u32 s18, s52, 0xfffc0080
	s_addc_u32 s54, s53, -1
	s_cmp_eq_u32 s71, 12
	s_cselect_b32 s57, s45, s54
	s_cselect_b32 s56, s67, s18
	s_cselect_b32 s55, s43, s70
	s_cselect_b32 s54, s68, s69
	v_lshl_add_u64 v[198:199], s[52:53], 0, v[152:153]
	s_add_i32 m0, s17, 0xc000
	ds_read_b128 v[166:169], v164
	ds_read_b128 v[170:173], v164 offset:1024
	ds_read_b128 v[174:177], v164 offset:2048
	ds_read_b128 v[178:181], v164 offset:3072
	ds_read_b128 v[182:185], v164 offset:4096
	ds_read_b128 v[186:189], v164 offset:5120
	ds_read_b128 v[190:193], v164 offset:6144
	ds_read_b128 v[194:197], v164 offset:7168
	global_load_lds_dwordx4 v[198:199], off
	v_lshl_add_u64 v[198:199], s[52:53], 0, v[154:155]
	s_add_i32 m0, s17, 0xe000
	s_nop 0
	global_load_lds_dwordx4 v[198:199], off
	s_waitcnt lgkmcnt(8)
	s_barrier
	s_waitcnt lgkmcnt(0)
	s_waitcnt lgkmcnt(0)
	v_mfma_f32_16x16x32_bf16 v[124:127], v[128:131], v[166:169], v[124:127]
	v_mfma_f32_16x16x32_bf16 v[120:123], v[136:139], v[166:169], v[120:123]
	v_mfma_f32_16x16x32_bf16 v[116:119], v[128:131], v[174:177], v[116:119]
	v_mfma_f32_16x16x32_bf16 v[112:115], v[136:139], v[174:177], v[112:115]
	v_mfma_f32_16x16x32_bf16 v[108:111], v[128:131], v[182:185], v[108:111]
	v_mfma_f32_16x16x32_bf16 v[100:103], v[136:139], v[182:185], v[100:103]
	v_mfma_f32_16x16x32_bf16 v[76:79], v[128:131], v[190:193], v[76:79]
	v_mfma_f32_16x16x32_bf16 v[72:75], v[136:139], v[190:193], v[72:75]
	v_mfma_f32_16x16x32_bf16 v[124:127], v[132:135], v[170:173], v[124:127]
	v_mfma_f32_16x16x32_bf16 v[120:123], v[140:143], v[170:173], v[120:123]
	v_mfma_f32_16x16x32_bf16 v[116:119], v[132:135], v[178:181], v[116:119]
	v_mfma_f32_16x16x32_bf16 v[112:115], v[140:143], v[178:181], v[112:115]
	v_mfma_f32_16x16x32_bf16 v[108:111], v[132:135], v[186:189], v[108:111]
	v_mfma_f32_16x16x32_bf16 v[100:103], v[140:143], v[186:189], v[100:103]
	v_mfma_f32_16x16x32_bf16 v[76:79], v[132:135], v[194:197], v[76:79]
	v_mfma_f32_16x16x32_bf16 v[72:75], v[140:143], v[194:197], v[72:75]
	s_barrier
	s_add_i32 s18, s59, s16
	v_lshl_add_u64 v[214:215], s[54:55], 0, v[148:149]
	s_mov_b32 m0, s18
	ds_read_b128 v[198:201], v165
	ds_read_b128 v[202:205], v165 offset:1024
	ds_read_b128 v[206:209], v165 offset:2048
	ds_read_b128 v[210:213], v165 offset:3072
	global_load_lds_dwordx4 v[214:215], off
	v_lshl_add_u64 v[216:217], s[54:55], 0, v[144:145]
	s_add_i32 m0, s18, 0x2000
	s_nop 0
	global_load_lds_dwordx4 v[216:217], off
	s_barrier
	s_waitcnt lgkmcnt(0)
	s_waitcnt lgkmcnt(0)
	v_mfma_f32_16x16x32_bf16 v[104:107], v[198:201], v[166:169], v[104:107]
	v_mfma_f32_16x16x32_bf16 v[96:99], v[206:209], v[166:169], v[96:99]
	v_mfma_f32_16x16x32_bf16 v[92:95], v[198:201], v[174:177], v[92:95]
	v_mfma_f32_16x16x32_bf16 v[88:91], v[206:209], v[174:177], v[88:91]
	v_mfma_f32_16x16x32_bf16 v[84:87], v[198:201], v[182:185], v[84:87]
	v_mfma_f32_16x16x32_bf16 v[80:83], v[206:209], v[182:185], v[80:83]
	v_mfma_f32_16x16x32_bf16 v[68:71], v[198:201], v[190:193], v[68:71]
	v_mfma_f32_16x16x32_bf16 v[64:67], v[206:209], v[190:193], v[64:67]
	v_mfma_f32_16x16x32_bf16 v[104:107], v[202:205], v[170:173], v[104:107]
	v_mfma_f32_16x16x32_bf16 v[96:99], v[210:213], v[170:173], v[96:99]
	v_mfma_f32_16x16x32_bf16 v[92:95], v[202:205], v[178:181], v[92:95]
	v_mfma_f32_16x16x32_bf16 v[88:91], v[210:213], v[178:181], v[88:91]
	v_mfma_f32_16x16x32_bf16 v[84:87], v[202:205], v[186:189], v[84:87]
	v_mfma_f32_16x16x32_bf16 v[80:83], v[210:213], v[186:189], v[80:83]
	v_mfma_f32_16x16x32_bf16 v[68:71], v[202:205], v[194:197], v[68:71]
	v_mfma_f32_16x16x32_bf16 v[64:67], v[210:213], v[194:197], v[64:67]
	s_mov_b32 m0, s17
	v_lshl_add_u64 v[218:219], s[56:57], 0, v[150:151]
	s_barrier
	ds_read_b128 v[166:169], v164 offset:16384
	ds_read_b128 v[170:173], v164 offset:17408
	ds_read_b128 v[174:177], v164 offset:18432
	ds_read_b128 v[178:181], v164 offset:19456
	ds_read_b128 v[182:185], v164 offset:20480
	ds_read_b128 v[186:189], v164 offset:21504
	ds_read_b128 v[190:193], v164 offset:22528
	ds_read_b128 v[194:197], v164 offset:23552
	global_load_lds_dwordx4 v[218:219], off
	v_lshl_add_u64 v[220:221], s[56:57], 0, v[146:147]
	s_mov_b32 m0, s19
	s_nop 0
	global_load_lds_dwordx4 v[220:221], off
	s_barrier
	s_waitcnt lgkmcnt(0)
	s_waitcnt lgkmcnt(0)
	v_mfma_f32_16x16x32_bf16 v[60:63], v[128:131], v[166:169], v[60:63]
	v_mfma_f32_16x16x32_bf16 v[56:59], v[136:139], v[166:169], v[56:59]
	v_mfma_f32_16x16x32_bf16 v[52:55], v[128:131], v[174:177], v[52:55]
	v_mfma_f32_16x16x32_bf16 v[44:47], v[136:139], v[174:177], v[44:47]
	v_mfma_f32_16x16x32_bf16 v[36:39], v[128:131], v[182:185], v[36:39]
	v_mfma_f32_16x16x32_bf16 v[28:31], v[136:139], v[182:185], v[28:31]
	v_mfma_f32_16x16x32_bf16 v[20:23], v[128:131], v[190:193], v[20:23]
	v_mfma_f32_16x16x32_bf16 v[12:15], v[136:139], v[190:193], v[12:15]
	v_mfma_f32_16x16x32_bf16 v[60:63], v[132:135], v[170:173], v[60:63]
	v_mfma_f32_16x16x32_bf16 v[56:59], v[140:143], v[170:173], v[56:59]
	v_mfma_f32_16x16x32_bf16 v[52:55], v[132:135], v[178:181], v[52:55]
	v_mfma_f32_16x16x32_bf16 v[44:47], v[140:143], v[178:181], v[44:47]
	v_mfma_f32_16x16x32_bf16 v[36:39], v[132:135], v[186:189], v[36:39]
	v_mfma_f32_16x16x32_bf16 v[28:31], v[140:143], v[186:189], v[28:31]
	v_mfma_f32_16x16x32_bf16 v[20:23], v[132:135], v[194:197], v[20:23]
	v_mfma_f32_16x16x32_bf16 v[12:15], v[140:143], v[194:197], v[12:15]
	s_barrier
	s_add_u32 s72, s54, 0x40000
	s_addc_u32 s73, s55, 0
	s_add_i32 s18, s60, s16
	v_lshl_add_u64 v[128:129], s[72:73], 0, v[148:149]
	s_mov_b32 m0, s18
	s_nop 0
	global_load_lds_dwordx4 v[128:129], off
	v_lshl_add_u64 v[128:129], s[72:73], 0, v[144:145]
	s_add_i32 m0, s18, 0x2000
	s_nop 0
	global_load_lds_dwordx4 v[128:129], off
	s_waitcnt vmcnt(6)
	s_barrier
	v_mfma_f32_16x16x32_bf16 v[48:51], v[198:201], v[166:169], v[48:51]
	v_mfma_f32_16x16x32_bf16 v[40:43], v[206:209], v[166:169], v[40:43]
	v_mfma_f32_16x16x32_bf16 v[32:35], v[198:201], v[174:177], v[32:35]
	v_mfma_f32_16x16x32_bf16 v[24:27], v[206:209], v[174:177], v[24:27]
	v_mfma_f32_16x16x32_bf16 v[16:19], v[198:201], v[182:185], v[16:19]
	v_mfma_f32_16x16x32_bf16 v[8:11], v[206:209], v[182:185], v[8:11]
	v_mfma_f32_16x16x32_bf16 v[4:7], v[198:201], v[190:193], v[4:7]
	v_mfma_f32_16x16x32_bf16 v[0:3], v[206:209], v[190:193], v[0:3]
	v_mfma_f32_16x16x32_bf16 v[48:51], v[202:205], v[170:173], v[48:51]
	v_mfma_f32_16x16x32_bf16 v[40:43], v[210:213], v[170:173], v[40:43]
	v_mfma_f32_16x16x32_bf16 v[32:35], v[202:205], v[178:181], v[32:35]
	v_mfma_f32_16x16x32_bf16 v[24:27], v[210:213], v[178:181], v[24:27]
	v_mfma_f32_16x16x32_bf16 v[16:19], v[202:205], v[186:189], v[16:19]
	v_mfma_f32_16x16x32_bf16 v[8:11], v[210:213], v[186:189], v[8:11]
	v_mfma_f32_16x16x32_bf16 v[4:7], v[202:205], v[194:197], v[4:7]
	v_mfma_f32_16x16x32_bf16 v[0:3], v[210:213], v[194:197], v[0:3]
	s_add_i32 s18, 0, 0x18000
	v_add_u32_e32 v140, s18, v161
	s_barrier
	ds_read_b128 v[128:131], v140
	ds_read_b128 v[132:135], v140 offset:1024
	ds_read_b128 v[136:139], v140 offset:2048
	ds_read_b128 v[140:143], v140 offset:3072
	s_add_u32 s56, s56, 0x40000
	s_addc_u32 s57, s57, 0
	s_mov_b32 m0, s28
	v_lshl_add_u64 v[198:199], s[56:57], 0, v[150:151]
	ds_read_b128 v[166:169], v164 offset:32768
	ds_read_b128 v[170:173], v164 offset:33792
	ds_read_b128 v[174:177], v164 offset:34816
	ds_read_b128 v[178:181], v164 offset:35840
	ds_read_b128 v[182:185], v164 offset:36864
	ds_read_b128 v[186:189], v164 offset:37888
	ds_read_b128 v[190:193], v164 offset:38912
	ds_read_b128 v[194:197], v164 offset:39936
	global_load_lds_dwordx4 v[198:199], off
	v_lshl_add_u64 v[198:199], s[56:57], 0, v[146:147]
	s_mov_b32 m0, s29
	s_nop 0
	global_load_lds_dwordx4 v[198:199], off
	s_waitcnt lgkmcnt(8)
	s_barrier
	s_waitcnt lgkmcnt(0)
	s_waitcnt lgkmcnt(0)
	v_mfma_f32_16x16x32_bf16 v[124:127], v[128:131], v[166:169], v[124:127]
	v_mfma_f32_16x16x32_bf16 v[120:123], v[136:139], v[166:169], v[120:123]
	v_mfma_f32_16x16x32_bf16 v[116:119], v[128:131], v[174:177], v[116:119]
	v_mfma_f32_16x16x32_bf16 v[112:115], v[136:139], v[174:177], v[112:115]
	v_mfma_f32_16x16x32_bf16 v[108:111], v[128:131], v[182:185], v[108:111]
	v_mfma_f32_16x16x32_bf16 v[100:103], v[136:139], v[182:185], v[100:103]
	v_mfma_f32_16x16x32_bf16 v[76:79], v[128:131], v[190:193], v[76:79]
	v_mfma_f32_16x16x32_bf16 v[72:75], v[136:139], v[190:193], v[72:75]
	v_mfma_f32_16x16x32_bf16 v[124:127], v[132:135], v[170:173], v[124:127]
	v_mfma_f32_16x16x32_bf16 v[120:123], v[140:143], v[170:173], v[120:123]
	v_mfma_f32_16x16x32_bf16 v[116:119], v[132:135], v[178:181], v[116:119]
	v_mfma_f32_16x16x32_bf16 v[112:115], v[140:143], v[178:181], v[112:115]
	v_mfma_f32_16x16x32_bf16 v[108:111], v[132:135], v[186:189], v[108:111]
	v_mfma_f32_16x16x32_bf16 v[100:103], v[140:143], v[186:189], v[100:103]
	v_mfma_f32_16x16x32_bf16 v[76:79], v[132:135], v[194:197], v[76:79]
	v_mfma_f32_16x16x32_bf16 v[72:75], v[140:143], v[194:197], v[72:75]
	s_barrier
	s_add_i32 s56, 0, 0x1c000
	s_add_i32 s18, s18, s16
	v_add_u32_e32 v210, s56, v161
	v_lshl_add_u64 v[214:215], v[214:215], 0, s[12:13]
	s_mov_b32 m0, s18
	ds_read_b128 v[198:201], v210
	ds_read_b128 v[202:205], v210 offset:1024
	ds_read_b128 v[206:209], v210 offset:2048
	ds_read_b128 v[210:213], v210 offset:3072
	global_load_lds_dwordx4 v[214:215], off
	v_lshl_add_u64 v[214:215], v[216:217], 0, s[12:13]
	s_add_i32 m0, s18, 0x2000
	s_nop 0
	global_load_lds_dwordx4 v[214:215], off
	s_barrier
	s_waitcnt lgkmcnt(0)
	s_waitcnt lgkmcnt(0)
	v_mfma_f32_16x16x32_bf16 v[104:107], v[198:201], v[166:169], v[104:107]
	v_mfma_f32_16x16x32_bf16 v[96:99], v[206:209], v[166:169], v[96:99]
	v_mfma_f32_16x16x32_bf16 v[92:95], v[198:201], v[174:177], v[92:95]
	v_mfma_f32_16x16x32_bf16 v[88:91], v[206:209], v[174:177], v[88:91]
	v_mfma_f32_16x16x32_bf16 v[84:87], v[198:201], v[182:185], v[84:87]
	v_mfma_f32_16x16x32_bf16 v[80:83], v[206:209], v[182:185], v[80:83]
	v_mfma_f32_16x16x32_bf16 v[68:71], v[198:201], v[190:193], v[68:71]
	v_mfma_f32_16x16x32_bf16 v[64:67], v[206:209], v[190:193], v[64:67]
	v_mfma_f32_16x16x32_bf16 v[104:107], v[202:205], v[170:173], v[104:107]
	v_mfma_f32_16x16x32_bf16 v[96:99], v[210:213], v[170:173], v[96:99]
	v_mfma_f32_16x16x32_bf16 v[92:95], v[202:205], v[178:181], v[92:95]
	v_mfma_f32_16x16x32_bf16 v[88:91], v[210:213], v[178:181], v[88:91]
	v_mfma_f32_16x16x32_bf16 v[84:87], v[202:205], v[186:189], v[84:87]
	v_mfma_f32_16x16x32_bf16 v[80:83], v[210:213], v[186:189], v[80:83]
	v_mfma_f32_16x16x32_bf16 v[68:71], v[202:205], v[194:197], v[68:71]
	v_mfma_f32_16x16x32_bf16 v[64:67], v[210:213], v[194:197], v[64:67]
	s_mov_b32 m0, s51
	v_lshl_add_u64 v[214:215], v[218:219], 0, s[12:13]
	s_barrier
	ds_read_b128 v[166:169], v164 offset:49152
	ds_read_b128 v[170:173], v164 offset:50176
	ds_read_b128 v[174:177], v164 offset:51200
	ds_read_b128 v[178:181], v164 offset:52224
	ds_read_b128 v[182:185], v164 offset:53248
	ds_read_b128 v[186:189], v164 offset:54272
	ds_read_b128 v[190:193], v164 offset:55296
	ds_read_b128 v[194:197], v164 offset:56320
	global_load_lds_dwordx4 v[214:215], off
	v_lshl_add_u64 v[214:215], v[220:221], 0, s[12:13]
	s_mov_b32 m0, s58
	s_nop 0
	global_load_lds_dwordx4 v[214:215], off
	s_barrier
	s_waitcnt lgkmcnt(0)
	s_waitcnt lgkmcnt(0)
	v_mfma_f32_16x16x32_bf16 v[60:63], v[128:131], v[166:169], v[60:63]
	v_mfma_f32_16x16x32_bf16 v[56:59], v[136:139], v[166:169], v[56:59]
	v_mfma_f32_16x16x32_bf16 v[52:55], v[128:131], v[174:177], v[52:55]
	v_mfma_f32_16x16x32_bf16 v[44:47], v[136:139], v[174:177], v[44:47]
	v_mfma_f32_16x16x32_bf16 v[36:39], v[128:131], v[182:185], v[36:39]
	v_mfma_f32_16x16x32_bf16 v[28:31], v[136:139], v[182:185], v[28:31]
	v_mfma_f32_16x16x32_bf16 v[20:23], v[128:131], v[190:193], v[20:23]
	v_mfma_f32_16x16x32_bf16 v[12:15], v[136:139], v[190:193], v[12:15]
	v_mfma_f32_16x16x32_bf16 v[60:63], v[132:135], v[170:173], v[60:63]
	v_mfma_f32_16x16x32_bf16 v[56:59], v[140:143], v[170:173], v[56:59]
	v_mfma_f32_16x16x32_bf16 v[52:55], v[132:135], v[178:181], v[52:55]
	v_mfma_f32_16x16x32_bf16 v[44:47], v[140:143], v[178:181], v[44:47]
	v_mfma_f32_16x16x32_bf16 v[36:39], v[132:135], v[186:189], v[36:39]
	v_mfma_f32_16x16x32_bf16 v[28:31], v[140:143], v[186:189], v[28:31]
	v_mfma_f32_16x16x32_bf16 v[20:23], v[132:135], v[194:197], v[20:23]
	v_mfma_f32_16x16x32_bf16 v[12:15], v[140:143], v[194:197], v[12:15]
	s_barrier
	s_add_u32 s54, s54, 0x40080
	s_addc_u32 s55, s55, 0
	s_add_i32 s18, s56, s16
	v_lshl_add_u64 v[128:129], s[54:55], 0, v[148:149]
	s_mov_b32 m0, s18
	s_nop 0
	global_load_lds_dwordx4 v[128:129], off
	v_lshl_add_u64 v[128:129], s[54:55], 0, v[144:145]
	s_add_i32 m0, s18, 0x2000
	s_nop 0
	global_load_lds_dwordx4 v[128:129], off
	s_waitcnt vmcnt(6)
	s_barrier
	v_mfma_f32_16x16x32_bf16 v[48:51], v[198:201], v[166:169], v[48:51]
	v_mfma_f32_16x16x32_bf16 v[40:43], v[206:209], v[166:169], v[40:43]
	v_mfma_f32_16x16x32_bf16 v[32:35], v[198:201], v[174:177], v[32:35]
	v_mfma_f32_16x16x32_bf16 v[24:27], v[206:209], v[174:177], v[24:27]
	v_mfma_f32_16x16x32_bf16 v[16:19], v[198:201], v[182:185], v[16:19]
	v_mfma_f32_16x16x32_bf16 v[8:11], v[206:209], v[182:185], v[8:11]
	v_mfma_f32_16x16x32_bf16 v[4:7], v[198:201], v[190:193], v[4:7]
	v_mfma_f32_16x16x32_bf16 v[0:3], v[206:209], v[190:193], v[0:3]
	v_mfma_f32_16x16x32_bf16 v[48:51], v[202:205], v[170:173], v[48:51]
	v_mfma_f32_16x16x32_bf16 v[40:43], v[210:213], v[170:173], v[40:43]
	v_mfma_f32_16x16x32_bf16 v[32:35], v[202:205], v[178:181], v[32:35]
	v_mfma_f32_16x16x32_bf16 v[24:27], v[210:213], v[178:181], v[24:27]
	v_mfma_f32_16x16x32_bf16 v[16:19], v[202:205], v[186:189], v[16:19]
	v_mfma_f32_16x16x32_bf16 v[8:11], v[210:213], v[186:189], v[8:11]
	v_mfma_f32_16x16x32_bf16 v[4:7], v[202:205], v[194:197], v[4:7]
	v_mfma_f32_16x16x32_bf16 v[0:3], v[210:213], v[194:197], v[0:3]
	s_add_i32 s71, s71, 2
	s_add_u32 s52, s52, 0x100
	s_addc_u32 s53, s53, 0
	s_add_u32 s69, s69, 0x100
	s_addc_u32 s70, s70, 0
	s_cmp_gt_u32 s71, 13
	s_barrier
	s_cbranch_scc0 .LBB0_1499
	s_sub_i32 s18, s50, 32
	s_lshr_b32 s18, s18, 2
	s_mulk_i32 s18, 0xc00
	s_addk_i32 s18, 0xc00
	s_cmp_gt_i32 s50, 31
	s_cselect_b32 s52, s18, 0
	s_ashr_i32 s53, s52, 31
	s_lshl_b64 s[52:53], s[52:53], 2
	v_lshl_or_b32 v166, s66, 8, v162
	s_add_u32 s52, s24, s52
	s_addc_u32 s53, s25, s53
	v_ashrrev_i32_e32 v167, 31, v166
	v_lshl_add_u64 v[128:129], v[166:167], 2, s[52:53]
	v_add_co_u32_e32 v130, vcc, s61, v128
	v_lshl_add_u32 v168, s50, 8, v160
	s_nop 0
	v_addc_co_u32_e32 v131, vcc, 0, v129, vcc
	global_load_dwordx4 v[140:143], v[130:131], off
	v_lshl_add_u64 v[128:129], v[128:129], 0, s[14:15]
	global_load_dwordx4 v[136:139], v[128:129], off offset:16
	global_load_dwordx4 v[132:135], v[128:129], off offset:512
	s_nop 0
	global_load_dwordx4 v[128:131], v[128:129], off offset:528
	v_ashrrev_i32_e32 v169, 31, v168
	v_or_b32_e32 v170, 16, v168
	v_or_b32_e32 v172, 32, v168
	v_or_b32_e32 v174, 48, v168
	v_lshlrev_b64 v[168:169], 11, v[168:169]
	v_ashrrev_i32_e32 v171, 31, v170
	v_ashrrev_i32_e32 v173, 31, v172
	v_lshlrev_b64 v[166:167], 1, v[166:167]
	v_ashrrev_i32_e32 v175, 31, v174
	v_lshl_add_u64 v[168:169], s[4:5], 0, v[168:169]
	v_lshlrev_b64 v[170:171], 11, v[170:171]
	v_lshlrev_b64 v[172:173], 11, v[172:173]
	v_lshlrev_b64 v[174:175], 11, v[174:175]
	v_lshl_add_u64 v[168:169], v[168:169], 0, v[166:167]
	v_lshl_add_u64 v[170:171], s[4:5], 0, v[170:171]
	v_lshl_add_u64 v[172:173], s[4:5], 0, v[172:173]
	v_lshl_add_u64 v[170:171], v[170:171], 0, v[166:167]
	v_lshl_add_u64 v[172:173], v[172:173], 0, v[166:167]
	s_mov_b32 s66, s42
	s_mov_b32 s50, s44
	s_mov_b64 s[54:55], s[48:49]
	s_mov_b64 s[52:53], s[46:47]
	s_waitcnt vmcnt(0)
	v_pk_mul_f32 v[122:123], v[122:123], v[138:139]
	v_pk_mul_f32 v[126:127], v[126:127], v[142:143]
	v_pk_mul_f32 v[124:125], v[124:125], v[140:141]
	v_pk_mul_f32 v[120:121], v[120:121], v[136:137]
	v_pk_mul_f32 v[106:107], v[106:107], v[134:135]
	v_pk_mul_f32 v[104:105], v[104:105], v[132:133]
	v_pk_mul_f32 v[98:99], v[98:99], v[130:131]
	v_pk_mul_f32 v[96:97], v[96:97], v[128:129]
	v_pk_mul_f32 v[118:119], v[118:119], v[142:143]
	v_pk_mul_f32 v[116:117], v[116:117], v[140:141]
	v_pk_mul_f32 v[114:115], v[114:115], v[138:139]
	v_pk_mul_f32 v[112:113], v[112:113], v[136:137]
	v_pk_mul_f32 v[94:95], v[94:95], v[134:135]
	v_pk_mul_f32 v[92:93], v[92:93], v[132:133]
	v_pk_mul_f32 v[176:177], v[90:91], v[130:131]
	v_pk_mul_f32 v[178:179], v[88:89], v[128:129]
	v_pk_mul_f32 v[110:111], v[110:111], v[142:143]
	v_pk_mul_f32 v[108:109], v[108:109], v[140:141]
	v_pk_mul_f32 v[102:103], v[102:103], v[138:139]
	v_pk_mul_f32 v[100:101], v[100:101], v[136:137]
	v_pk_mul_f32 v[180:181], v[86:87], v[134:135]
	v_pk_mul_f32 v[182:183], v[84:85], v[132:133]
	v_pk_mul_f32 v[184:185], v[82:83], v[130:131]
	v_pk_mul_f32 v[186:187], v[80:81], v[128:129]
	v_cvt_pk_bf16_f32 v80, v124, v125
	v_cvt_pk_bf16_f32 v81, v126, v127
	v_cvt_pk_bf16_f32 v82, v120, v121
	v_cvt_pk_bf16_f32 v83, v122, v123
	v_cvt_pk_bf16_f32 v84, v104, v105
	v_cvt_pk_bf16_f32 v85, v106, v107
	v_cvt_pk_bf16_f32 v86, v96, v97
	v_cvt_pk_bf16_f32 v87, v98, v99
	v_cvt_pk_bf16_f32 v88, v116, v117
	v_cvt_pk_bf16_f32 v89, v118, v119
	v_cvt_pk_bf16_f32 v90, v112, v113
	v_cvt_pk_bf16_f32 v91, v114, v115
	v_cvt_pk_bf16_f32 v92, v92, v93
	v_cvt_pk_bf16_f32 v93, v94, v95
	v_cvt_pk_bf16_f32 v94, v178, v179
	v_cvt_pk_bf16_f32 v95, v176, v177
	v_cvt_pk_bf16_f32 v96, v108, v109
	v_cvt_pk_bf16_f32 v97, v110, v111
	v_cvt_pk_bf16_f32 v98, v100, v101
	v_cvt_pk_bf16_f32 v99, v102, v103
	v_cvt_pk_bf16_f32 v100, v182, v183
	v_cvt_pk_bf16_f32 v101, v180, v181
	v_cvt_pk_bf16_f32 v102, v186, v187
	v_cvt_pk_bf16_f32 v103, v184, v185
	global_store_dwordx4 v[168:169], v[80:83], off
	global_store_dwordx4 v[168:169], v[84:87], off offset:256
	global_store_dwordx4 v[170:171], v[88:91], off
	global_store_dwordx4 v[170:171], v[92:95], off offset:256
	global_store_dwordx4 v[172:173], v[96:99], off
	global_store_dwordx4 v[172:173], v[100:103], off offset:256
	v_lshl_add_u64 v[80:81], s[4:5], 0, v[174:175]
	v_pk_mul_f32 v[78:79], v[78:79], v[142:143]
	v_pk_mul_f32 v[76:77], v[76:77], v[140:141]
	v_pk_mul_f32 v[82:83], v[74:75], v[138:139]
	v_pk_mul_f32 v[74:75], v[72:73], v[136:137]
	v_lshl_add_u64 v[80:81], v[80:81], 0, v[166:167]
	v_cvt_pk_bf16_f32 v72, v76, v77
	v_cvt_pk_bf16_f32 v73, v78, v79
	v_cvt_pk_bf16_f32 v74, v74, v75
	v_cvt_pk_bf16_f32 v75, v82, v83
	global_store_dwordx4 v[80:81], v[72:75], off
	v_pk_mul_f32 v[70:71], v[70:71], v[134:135]
	v_pk_mul_f32 v[68:69], v[68:69], v[132:133]
	v_pk_mul_f32 v[72:73], v[66:67], v[130:131]
	v_pk_mul_f32 v[66:67], v[64:65], v[128:129]
	v_cvt_pk_bf16_f32 v64, v68, v69
	v_cvt_pk_bf16_f32 v65, v70, v71
	v_cvt_pk_bf16_f32 v66, v66, v67
	v_cvt_pk_bf16_f32 v67, v72, v73
	v_pk_mul_f32 v[60:61], v[60:61], v[140:141]
	global_store_dwordx4 v[80:81], v[64:67], off offset:256
	v_pk_mul_f32 v[62:63], v[62:63], v[142:143]
	v_pk_mul_f32 v[50:51], v[50:51], v[134:135]
	v_pk_mul_f32 v[66:67], v[58:59], v[138:139]
	v_pk_mul_f32 v[58:59], v[56:57], v[136:137]
	v_cvt_pk_bf16_f32 v56, v60, v61
	v_add_co_u32_e32 v60, vcc, s62, v168
	v_cvt_pk_bf16_f32 v57, v62, v63
	v_cvt_pk_bf16_f32 v58, v58, v59
	v_cvt_pk_bf16_f32 v59, v66, v67
	v_addc_co_u32_e32 v61, vcc, 0, v169, vcc
	global_store_dwordx4 v[60:61], v[56:59], off
	v_pk_mul_f32 v[48:49], v[48:49], v[132:133]
	v_lshl_add_u64 v[64:65], v[168:169], 0, s[6:7]
	v_pk_mul_f32 v[56:57], v[42:43], v[130:131]
	v_pk_mul_f32 v[42:43], v[40:41], v[128:129]
	v_cvt_pk_bf16_f32 v40, v48, v49
	v_cvt_pk_bf16_f32 v41, v50, v51
	v_cvt_pk_bf16_f32 v42, v42, v43
	v_cvt_pk_bf16_f32 v43, v56, v57
	global_store_dwordx4 v[64:65], v[40:43], off offset:256
	v_pk_mul_f32 v[44:45], v[44:45], v[136:137]
	v_pk_mul_f32 v[46:47], v[46:47], v[138:139]
	v_pk_mul_f32 v[42:43], v[54:55], v[142:143]
	v_pk_mul_f32 v[40:41], v[52:53], v[140:141]
	v_pk_mul_f32 v[34:35], v[34:35], v[134:135]
	v_cvt_pk_bf16_f32 v40, v40, v41
	v_cvt_pk_bf16_f32 v41, v42, v43
	v_cvt_pk_bf16_f32 v42, v44, v45
	v_add_co_u32_e32 v44, vcc, s63, v168
	v_cvt_pk_bf16_f32 v43, v46, v47
	s_nop 0
	v_addc_co_u32_e32 v45, vcc, 0, v169, vcc
	global_store_dwordx4 v[44:45], v[40:43], off
	v_pk_mul_f32 v[32:33], v[32:33], v[132:133]
	v_lshl_add_u64 v[48:49], v[168:169], 0, s[36:37]
	v_pk_mul_f32 v[40:41], v[26:27], v[130:131]
	v_pk_mul_f32 v[26:27], v[24:25], v[128:129]
	v_cvt_pk_bf16_f32 v24, v32, v33
	v_cvt_pk_bf16_f32 v25, v34, v35
	v_cvt_pk_bf16_f32 v26, v26, v27
	v_cvt_pk_bf16_f32 v27, v40, v41
	global_store_dwordx4 v[48:49], v[24:27], off offset:256
	v_pk_mul_f32 v[28:29], v[28:29], v[136:137]
	v_pk_mul_f32 v[30:31], v[30:31], v[138:139]
	v_pk_mul_f32 v[26:27], v[38:39], v[142:143]
	v_pk_mul_f32 v[24:25], v[36:37], v[140:141]
	v_pk_mul_f32 v[18:19], v[18:19], v[134:135]
	v_cvt_pk_bf16_f32 v24, v24, v25
	v_cvt_pk_bf16_f32 v25, v26, v27
	v_cvt_pk_bf16_f32 v26, v28, v29
	v_add_co_u32_e32 v28, vcc, s64, v168
	v_cvt_pk_bf16_f32 v27, v30, v31
	s_nop 0
	v_addc_co_u32_e32 v29, vcc, 0, v169, vcc
	global_store_dwordx4 v[28:29], v[24:27], off
	v_pk_mul_f32 v[16:17], v[16:17], v[132:133]
	v_lshl_add_u64 v[32:33], v[168:169], 0, s[38:39]
	v_pk_mul_f32 v[24:25], v[10:11], v[130:131]
	v_pk_mul_f32 v[10:11], v[8:9], v[128:129]
	v_cvt_pk_bf16_f32 v8, v16, v17
	v_cvt_pk_bf16_f32 v9, v18, v19
	v_cvt_pk_bf16_f32 v10, v10, v11
	v_cvt_pk_bf16_f32 v11, v24, v25
	global_store_dwordx4 v[32:33], v[8:11], off offset:256
	v_pk_mul_f32 v[12:13], v[12:13], v[136:137]
	v_pk_mul_f32 v[14:15], v[14:15], v[138:139]
	v_pk_mul_f32 v[10:11], v[22:23], v[142:143]
	v_pk_mul_f32 v[8:9], v[20:21], v[140:141]
	v_pk_mul_f32 v[6:7], v[6:7], v[134:135]
	v_cvt_pk_bf16_f32 v8, v8, v9
	v_cvt_pk_bf16_f32 v9, v10, v11
	v_cvt_pk_bf16_f32 v10, v12, v13
	v_add_co_u32_e32 v12, vcc, s65, v168
	v_cvt_pk_bf16_f32 v11, v14, v15
	s_nop 0
	v_addc_co_u32_e32 v13, vcc, 0, v169, vcc
	global_store_dwordx4 v[12:13], v[8:11], off
	v_pk_mul_f32 v[4:5], v[4:5], v[132:133]
	v_lshl_add_u64 v[16:17], v[168:169], 0, s[40:41]
	v_pk_mul_f32 v[8:9], v[2:3], v[130:131]
	v_pk_mul_f32 v[2:3], v[0:1], v[128:129]
	v_cvt_pk_bf16_f32 v0, v4, v5
	v_cvt_pk_bf16_f32 v1, v6, v7
	v_cvt_pk_bf16_f32 v2, v2, v3
	v_cvt_pk_bf16_f32 v3, v8, v9
	s_and_b64 vcc, exec, s[0:1]
	global_store_dwordx4 v[16:17], v[0:3], off offset:256
	s_cbranch_vccz .LBB0_1496
	s_waitcnt vmcnt(0)
	s_cmpk_gt_u32 s3, 0xff
	s_cbranch_scc1 .LBB0_1503
	s_barrier
